# instruction-fetch warming: at each GEMM K-loop exit (and at the first K-loop's entry) the workgroup reads the next 64 KiB of code as data (LDS-DMA into an unused LDS area), so the branchy epilogue's c
# speedup vs baseline: 1.0423x; 1.0126x over previous
.LBB0_351:
	s_ashr_i32 s51, s50, 31
	s_lshl_b64 s[12:13], s[50:51], 19
	s_cmp_eq_u32 s0, 1
	s_cselect_b32 s3, s84, s17
	s_cselect_b32 s1, s85, s49
	s_cselect_b32 s14, s17, s84
	s_cselect_b32 s15, s49, s85
	s_add_u32 s56, s3, s12
	s_addc_u32 s57, s1, s13
	s_ashr_i32 s53, s52, 31
	s_lshl_b64 s[12:13], s[52:53], 19
	s_add_u32 s58, s14, s12
	v_mov_b32_e32 v125, 0
	s_addc_u32 s59, s15, s13
	s_andn2_b64 vcc, exec, s[28:29]
	v_mov_b32_e32 v124, v125
	v_mov_b32_e32 v123, v125
	v_mov_b32_e32 v122, v125
	v_mov_b32_e32 v129, v125
	v_mov_b32_e32 v128, v125
	v_mov_b32_e32 v127, v125
	v_mov_b32_e32 v126, v125
	v_mov_b32_e32 v121, v125
	v_mov_b32_e32 v120, v125
	v_mov_b32_e32 v119, v125
	v_mov_b32_e32 v118, v125
	v_mov_b32_e32 v117, v125
	v_mov_b32_e32 v116, v125
	v_mov_b32_e32 v115, v125
	v_mov_b32_e32 v114, v125
	v_mov_b32_e32 v113, v125
	v_mov_b32_e32 v112, v125
	v_mov_b32_e32 v111, v125
	v_mov_b32_e32 v110, v125
	v_mov_b32_e32 v109, v125
	v_mov_b32_e32 v108, v125
	v_mov_b32_e32 v107, v125
	v_mov_b32_e32 v106, v125
	v_mov_b32_e32 v105, v125
	v_mov_b32_e32 v104, v125
	v_mov_b32_e32 v103, v125
	v_mov_b32_e32 v102, v125
	v_mov_b32_e32 v101, v125
	v_mov_b32_e32 v100, v125
	v_mov_b32_e32 v99, v125
	v_mov_b32_e32 v98, v125
	v_mov_b32_e32 v65, v125
	v_mov_b32_e32 v64, v125
	v_mov_b32_e32 v63, v125
	v_mov_b32_e32 v62, v125
	v_mov_b32_e32 v61, v125
	v_mov_b32_e32 v60, v125
	v_mov_b32_e32 v59, v125
	v_mov_b32_e32 v58, v125
	v_mov_b32_e32 v57, v125
	v_mov_b32_e32 v56, v125
	v_mov_b32_e32 v55, v125
	v_mov_b32_e32 v54, v125
	v_mov_b32_e32 v53, v125
	v_mov_b32_e32 v52, v125
	v_mov_b32_e32 v51, v125
	v_mov_b32_e32 v50, v125
	v_mov_b32_e32 v49, v125
	v_mov_b32_e32 v48, v125
	v_mov_b32_e32 v47, v125
	v_mov_b32_e32 v46, v125
	v_mov_b32_e32 v45, v125
	v_mov_b32_e32 v44, v125
	v_mov_b32_e32 v43, v125
	v_mov_b32_e32 v42, v125
	v_mov_b32_e32 v41, v125
	v_mov_b32_e32 v40, v125
	v_mov_b32_e32 v39, v125
	v_mov_b32_e32 v38, v125
	v_mov_b32_e32 v37, v125
	v_mov_b32_e32 v36, v125
	v_mov_b32_e32 v35, v125
	v_mov_b32_e32 v34, v125
	v_mov_b32_e32 v97, v125
	v_mov_b32_e32 v96, v125
	v_mov_b32_e32 v95, v125
	v_mov_b32_e32 v94, v125
	v_mov_b32_e32 v93, v125
	v_mov_b32_e32 v92, v125
	v_mov_b32_e32 v91, v125
	v_mov_b32_e32 v90, v125
	v_mov_b32_e32 v89, v125
	v_mov_b32_e32 v88, v125
	v_mov_b32_e32 v87, v125
	v_mov_b32_e32 v86, v125
	v_mov_b32_e32 v85, v125
	v_mov_b32_e32 v84, v125
	v_mov_b32_e32 v83, v125
	v_mov_b32_e32 v82, v125
	v_mov_b32_e32 v81, v125
	v_mov_b32_e32 v80, v125
	v_mov_b32_e32 v79, v125
	v_mov_b32_e32 v78, v125
	v_mov_b32_e32 v77, v125
	v_mov_b32_e32 v76, v125
	v_mov_b32_e32 v75, v125
	v_mov_b32_e32 v74, v125
	v_mov_b32_e32 v73, v125
	v_mov_b32_e32 v72, v125
	v_mov_b32_e32 v71, v125
	v_mov_b32_e32 v70, v125
	v_mov_b32_e32 v69, v125
	v_mov_b32_e32 v68, v125
	v_mov_b32_e32 v67, v125
	v_mov_b32_e32 v66, v125
	v_mov_b32_e32 v33, v125
	v_mov_b32_e32 v32, v125
	v_mov_b32_e32 v31, v125
	v_mov_b32_e32 v30, v125
	v_mov_b32_e32 v29, v125
	v_mov_b32_e32 v28, v125
	v_mov_b32_e32 v27, v125
	v_mov_b32_e32 v26, v125
	v_mov_b32_e32 v25, v125
	v_mov_b32_e32 v24, v125
	v_mov_b32_e32 v23, v125
	v_mov_b32_e32 v22, v125
	v_mov_b32_e32 v21, v125
	v_mov_b32_e32 v20, v125
	v_mov_b32_e32 v19, v125
	v_mov_b32_e32 v18, v125
	v_mov_b32_e32 v17, v125
	v_mov_b32_e32 v16, v125
	v_mov_b32_e32 v15, v125
	v_mov_b32_e32 v14, v125
	v_mov_b32_e32 v13, v125
	v_mov_b32_e32 v12, v125
	v_mov_b32_e32 v11, v125
	v_mov_b32_e32 v10, v125
	v_mov_b32_e32 v9, v125
	v_mov_b32_e32 v8, v125
	v_mov_b32_e32 v7, v125
	v_mov_b32_e32 v6, v125
	v_mov_b32_e32 v5, v125
	v_mov_b32_e32 v4, v125
	v_mov_b32_e32 v3, v125
	v_mov_b32_e32 v2, v125
	s_cbranch_vccnz .LBB0_354
	s_and_b64 s[12:13], s[54:55], exec
	s_cselect_b32 s1, s57, s9
	s_cselect_b32 s3, s56, s8
	s_cselect_b32 s12, s59, s11
	s_cselect_b32 s13, s58, s10
	s_add_u32 s8, s8, 0x80
	s_addc_u32 s9, s9, 0
	s_add_u32 s14, s10, 0x100
	v_mov_b32_e32 v2, 0
	s_addc_u32 s15, s11, 0
	s_mov_b32 s10, 0
	v_mov_b32_e32 v3, v2
	v_mov_b32_e32 v4, v2
	v_mov_b32_e32 v5, v2
	v_mov_b32_e32 v6, v2
	v_mov_b32_e32 v7, v2
	v_mov_b32_e32 v8, v2
	v_mov_b32_e32 v9, v2
	v_mov_b32_e32 v10, v2
	v_mov_b32_e32 v11, v2
	v_mov_b32_e32 v12, v2
	v_mov_b32_e32 v13, v2
	v_mov_b32_e32 v14, v2
	v_mov_b32_e32 v15, v2
	v_mov_b32_e32 v16, v2
	v_mov_b32_e32 v17, v2
	v_mov_b32_e32 v18, v2
	v_mov_b32_e32 v19, v2
	v_mov_b32_e32 v20, v2
	v_mov_b32_e32 v21, v2
	v_mov_b32_e32 v22, v2
	v_mov_b32_e32 v23, v2
	v_mov_b32_e32 v24, v2
	v_mov_b32_e32 v25, v2
	v_mov_b32_e32 v26, v2
	v_mov_b32_e32 v27, v2
	v_mov_b32_e32 v28, v2
	v_mov_b32_e32 v29, v2
	v_mov_b32_e32 v30, v2
	v_mov_b32_e32 v31, v2
	v_mov_b32_e32 v32, v2
	v_mov_b32_e32 v33, v2
	v_mov_b32_e32 v66, v2
	v_mov_b32_e32 v67, v2
	v_mov_b32_e32 v68, v2
	v_mov_b32_e32 v69, v2
	v_mov_b32_e32 v70, v2
	v_mov_b32_e32 v71, v2
	v_mov_b32_e32 v72, v2
	v_mov_b32_e32 v73, v2
	v_mov_b32_e32 v74, v2
	v_mov_b32_e32 v75, v2
	v_mov_b32_e32 v76, v2
	v_mov_b32_e32 v77, v2
	v_mov_b32_e32 v78, v2
	v_mov_b32_e32 v79, v2
	v_mov_b32_e32 v80, v2
	v_mov_b32_e32 v81, v2
	v_mov_b32_e32 v82, v2
	v_mov_b32_e32 v83, v2
	v_mov_b32_e32 v84, v2
	v_mov_b32_e32 v85, v2
	v_mov_b32_e32 v86, v2
	v_mov_b32_e32 v87, v2
	v_mov_b32_e32 v88, v2
	v_mov_b32_e32 v89, v2
	v_mov_b32_e32 v90, v2
	v_mov_b32_e32 v91, v2
	v_mov_b32_e32 v92, v2
	v_mov_b32_e32 v93, v2
	v_mov_b32_e32 v94, v2
	v_mov_b32_e32 v95, v2
	v_mov_b32_e32 v96, v2
	v_mov_b32_e32 v97, v2
	v_mov_b32_e32 v34, v2
	v_mov_b32_e32 v35, v2
	v_mov_b32_e32 v36, v2
	v_mov_b32_e32 v37, v2
	v_mov_b32_e32 v38, v2
	v_mov_b32_e32 v39, v2
	v_mov_b32_e32 v40, v2
	v_mov_b32_e32 v41, v2
	v_mov_b32_e32 v42, v2
	v_mov_b32_e32 v43, v2
	v_mov_b32_e32 v44, v2
	v_mov_b32_e32 v45, v2
	v_mov_b32_e32 v46, v2
	v_mov_b32_e32 v47, v2
	v_mov_b32_e32 v48, v2
	v_mov_b32_e32 v49, v2
	v_mov_b32_e32 v50, v2
	v_mov_b32_e32 v51, v2
	v_mov_b32_e32 v52, v2
	v_mov_b32_e32 v53, v2
	v_mov_b32_e32 v54, v2
	v_mov_b32_e32 v55, v2
	v_mov_b32_e32 v56, v2
	v_mov_b32_e32 v57, v2
	v_mov_b32_e32 v58, v2
	v_mov_b32_e32 v59, v2
	v_mov_b32_e32 v60, v2
	v_mov_b32_e32 v61, v2
	v_mov_b32_e32 v62, v2
	v_mov_b32_e32 v63, v2
	v_mov_b32_e32 v64, v2
	v_mov_b32_e32 v65, v2
	v_mov_b32_e32 v98, v2
	v_mov_b32_e32 v99, v2
	v_mov_b32_e32 v100, v2
	v_mov_b32_e32 v101, v2
	v_mov_b32_e32 v102, v2
	v_mov_b32_e32 v103, v2
	v_mov_b32_e32 v104, v2
	v_mov_b32_e32 v105, v2
	v_mov_b32_e32 v106, v2
	v_mov_b32_e32 v107, v2
	v_mov_b32_e32 v108, v2
	v_mov_b32_e32 v109, v2
	v_mov_b32_e32 v110, v2
	v_mov_b32_e32 v111, v2
	v_mov_b32_e32 v112, v2
	v_mov_b32_e32 v113, v2
	v_mov_b32_e32 v114, v2
	v_mov_b32_e32 v115, v2
	v_mov_b32_e32 v116, v2
	v_mov_b32_e32 v117, v2
	v_mov_b32_e32 v118, v2
	v_mov_b32_e32 v119, v2
	v_mov_b32_e32 v120, v2
	v_mov_b32_e32 v121, v2
	v_mov_b32_e32 v126, v2
	v_mov_b32_e32 v127, v2
	v_mov_b32_e32 v128, v2
	v_mov_b32_e32 v129, v2
	v_mov_b32_e32 v122, v2
	v_mov_b32_e32 v123, v2
	v_mov_b32_e32 v124, v2
	v_mov_b32_e32 v125, v2
	s_getpc_b64 s[98:99]
	s_add_u32 s98, s98, 0x800
	s_addc_u32 s99, s99, 0
	s_mov_b32 m0, 0x22800
	v_lshlrev_b32_e32 v232, 7, v0
	global_load_lds_dword v232, s[98:99]
.LBB0_353:
	s_waitcnt lgkmcnt(0)
	ds_read_b128 v[130:133], v189
	ds_read_b128 v[168:171], v189 offset:1024
	ds_read_b128 v[172:175], v189 offset:2048
	ds_read_b128 v[176:179], v189 offset:3072
	ds_read_b128 v[180:183], v190
	ds_read_b128 v[184:187], v190 offset:1024
	ds_read_b128 v[194:197], v190 offset:2048
	ds_read_b128 v[200:203], v190 offset:3072
	s_add_i32 s40, s10, 2
	s_add_u32 s41, s8, 0x80
	s_addc_u32 s11, s9, 0
	s_cmp_eq_u32 s87, s10
	s_cselect_b32 s10, s3, s41
	s_cselect_b32 s11, s1, s11
	s_cselect_b32 s61, s12, s15
	s_cselect_b32 s60, s13, s14
	v_lshl_add_u64 v[236:237], s[8:9], 0, v[164:165]
	s_add_i32 m0, s23, 0xc000
	ds_read_b128 v[204:207], v188
	ds_read_b128 v[208:211], v188 offset:1024
	ds_read_b128 v[212:215], v188 offset:2048
	ds_read_b128 v[216:219], v188 offset:3072
	ds_read_b128 v[220:223], v188 offset:4096
	ds_read_b128 v[224:227], v188 offset:5120
	ds_read_b128 v[228:231], v188 offset:6144
	ds_read_b128 v[232:235], v188 offset:7168
	global_load_lds_dwordx4 v[236:237], off
	v_lshl_add_u64 v[236:237], s[8:9], 0, v[166:167]
	s_add_i32 m0, s23, 0xe000
	s_nop 0
	global_load_lds_dwordx4 v[236:237], off
	s_waitcnt vmcnt(8)
	s_waitcnt lgkmcnt(0)
	s_barrier
	s_setprio 1
	s_waitcnt lgkmcnt(0)
	v_mfma_f32_16x16x32_bf16 v[122:125], v[130:133], v[204:207], v[122:125]
	v_mfma_f32_16x16x32_bf16 v[126:129], v[172:175], v[204:207], v[126:129]
	v_mfma_f32_16x16x32_bf16 v[118:121], v[130:133], v[212:215], v[118:121]
	v_mfma_f32_16x16x32_bf16 v[114:117], v[172:175], v[212:215], v[114:117]
	v_mfma_f32_16x16x32_bf16 v[110:113], v[130:133], v[220:223], v[110:113]
	v_mfma_f32_16x16x32_bf16 v[106:109], v[172:175], v[220:223], v[106:109]
	v_mfma_f32_16x16x32_bf16 v[102:105], v[130:133], v[228:231], v[102:105]
	v_mfma_f32_16x16x32_bf16 v[98:101], v[172:175], v[228:231], v[98:101]
	v_mfma_f32_16x16x32_bf16 v[122:125], v[168:171], v[208:211], v[122:125]
	v_mfma_f32_16x16x32_bf16 v[126:129], v[176:179], v[208:211], v[126:129]
	v_mfma_f32_16x16x32_bf16 v[118:121], v[168:171], v[216:219], v[118:121]
	v_mfma_f32_16x16x32_bf16 v[114:117], v[176:179], v[216:219], v[114:117]
	v_mfma_f32_16x16x32_bf16 v[110:113], v[168:171], v[224:227], v[110:113]
	v_mfma_f32_16x16x32_bf16 v[106:109], v[176:179], v[224:227], v[106:109]
	v_mfma_f32_16x16x32_bf16 v[102:105], v[168:171], v[232:235], v[102:105]
	v_mfma_f32_16x16x32_bf16 v[98:101], v[176:179], v[232:235], v[98:101]
	s_setprio 0
	s_setprio 1
	v_mfma_f32_16x16x32_bf16 v[62:65], v[180:183], v[204:207], v[62:65]
	v_mfma_f32_16x16x32_bf16 v[58:61], v[194:197], v[204:207], v[58:61]
	v_mfma_f32_16x16x32_bf16 v[54:57], v[180:183], v[212:215], v[54:57]
	v_mfma_f32_16x16x32_bf16 v[50:53], v[194:197], v[212:215], v[50:53]
	v_mfma_f32_16x16x32_bf16 v[46:49], v[180:183], v[220:223], v[46:49]
	v_mfma_f32_16x16x32_bf16 v[42:45], v[194:197], v[220:223], v[42:45]
	v_mfma_f32_16x16x32_bf16 v[38:41], v[180:183], v[228:231], v[38:41]
	v_mfma_f32_16x16x32_bf16 v[34:37], v[194:197], v[228:231], v[34:37]
	v_mfma_f32_16x16x32_bf16 v[62:65], v[184:187], v[208:211], v[62:65]
	v_mfma_f32_16x16x32_bf16 v[58:61], v[200:203], v[208:211], v[58:61]
	v_mfma_f32_16x16x32_bf16 v[54:57], v[184:187], v[216:219], v[54:57]
	v_mfma_f32_16x16x32_bf16 v[50:53], v[200:203], v[216:219], v[50:53]
	v_mfma_f32_16x16x32_bf16 v[46:49], v[184:187], v[224:227], v[46:49]
	v_mfma_f32_16x16x32_bf16 v[42:45], v[200:203], v[224:227], v[42:45]
	v_mfma_f32_16x16x32_bf16 v[38:41], v[184:187], v[232:235], v[38:41]
	v_mfma_f32_16x16x32_bf16 v[34:37], v[200:203], v[232:235], v[34:37]
	s_setprio 0
	s_barrier
	s_add_i32 s41, s86, s90
	v_lshl_add_u64 v[236:237], s[60:61], 0, v[136:137]
	s_mov_b32 m0, s41
	ds_read_b128 v[204:207], v188 offset:16384
	ds_read_b128 v[208:211], v188 offset:17408
	ds_read_b128 v[212:215], v188 offset:18432
	ds_read_b128 v[216:219], v188 offset:19456
	ds_read_b128 v[220:223], v188 offset:20480
	ds_read_b128 v[224:227], v188 offset:21504
	ds_read_b128 v[228:231], v188 offset:22528
	ds_read_b128 v[232:235], v188 offset:23552
	global_load_lds_dwordx4 v[236:237], off
	s_add_i32 m0, s41, 0x2000
	v_lshl_add_u64 v[238:239], s[60:61], 0, v[140:141]
	s_add_u32 s60, s60, s20
	s_addc_u32 s61, s61, s21
	s_add_i32 s41, s33, s90
	global_load_lds_dwordx4 v[238:239], off
	v_lshl_add_u64 v[240:241], s[60:61], 0, v[136:137]
	s_mov_b32 m0, s41
	v_lshl_add_u64 v[242:243], s[60:61], 0, v[140:141]
	global_load_lds_dwordx4 v[240:241], off
	s_add_i32 m0, s41, 0x2000
	v_lshl_add_u64 v[244:245], s[10:11], 0, v[134:135]
	global_load_lds_dwordx4 v[242:243], off
	s_mov_b32 m0, s23
	v_lshl_add_u64 v[246:247], s[10:11], 0, v[138:139]
	global_load_lds_dwordx4 v[244:245], off
	s_mov_b32 m0, s31
	s_nop 0
	global_load_lds_dwordx4 v[246:247], off
	s_waitcnt vmcnt(8)
	s_waitcnt lgkmcnt(0)
	s_barrier
	s_setprio 1
	s_waitcnt lgkmcnt(0)
	v_mfma_f32_16x16x32_bf16 v[94:97], v[130:133], v[204:207], v[94:97]
	v_mfma_f32_16x16x32_bf16 v[90:93], v[172:175], v[204:207], v[90:93]
	v_mfma_f32_16x16x32_bf16 v[86:89], v[130:133], v[212:215], v[86:89]
	v_mfma_f32_16x16x32_bf16 v[82:85], v[172:175], v[212:215], v[82:85]
	v_mfma_f32_16x16x32_bf16 v[78:81], v[130:133], v[220:223], v[78:81]
	v_mfma_f32_16x16x32_bf16 v[74:77], v[172:175], v[220:223], v[74:77]
	v_mfma_f32_16x16x32_bf16 v[70:73], v[130:133], v[228:231], v[70:73]
	v_mfma_f32_16x16x32_bf16 v[66:69], v[172:175], v[228:231], v[66:69]
	v_mfma_f32_16x16x32_bf16 v[94:97], v[168:171], v[208:211], v[94:97]
	v_mfma_f32_16x16x32_bf16 v[90:93], v[176:179], v[208:211], v[90:93]
	v_mfma_f32_16x16x32_bf16 v[86:89], v[168:171], v[216:219], v[86:89]
	v_mfma_f32_16x16x32_bf16 v[82:85], v[176:179], v[216:219], v[82:85]
	v_mfma_f32_16x16x32_bf16 v[78:81], v[168:171], v[224:227], v[78:81]
	v_mfma_f32_16x16x32_bf16 v[74:77], v[176:179], v[224:227], v[74:77]
	v_mfma_f32_16x16x32_bf16 v[70:73], v[168:171], v[232:235], v[70:73]
	v_mfma_f32_16x16x32_bf16 v[66:69], v[176:179], v[232:235], v[66:69]
	s_setprio 0
	s_setprio 1
	v_mfma_f32_16x16x32_bf16 v[30:33], v[180:183], v[204:207], v[30:33]
	v_mfma_f32_16x16x32_bf16 v[26:29], v[194:197], v[204:207], v[26:29]
	v_mfma_f32_16x16x32_bf16 v[22:25], v[180:183], v[212:215], v[22:25]
	v_mfma_f32_16x16x32_bf16 v[18:21], v[194:197], v[212:215], v[18:21]
	v_mfma_f32_16x16x32_bf16 v[14:17], v[180:183], v[220:223], v[14:17]
	v_mfma_f32_16x16x32_bf16 v[10:13], v[194:197], v[220:223], v[10:13]
	v_mfma_f32_16x16x32_bf16 v[6:9], v[180:183], v[228:231], v[6:9]
	v_mfma_f32_16x16x32_bf16 v[2:5], v[194:197], v[228:231], v[2:5]
	v_mfma_f32_16x16x32_bf16 v[30:33], v[184:187], v[208:211], v[30:33]
	v_mfma_f32_16x16x32_bf16 v[26:29], v[200:203], v[208:211], v[26:29]
	v_mfma_f32_16x16x32_bf16 v[22:25], v[184:187], v[216:219], v[22:25]
	v_mfma_f32_16x16x32_bf16 v[18:21], v[200:203], v[216:219], v[18:21]
	v_mfma_f32_16x16x32_bf16 v[14:17], v[184:187], v[224:227], v[14:17]
	v_mfma_f32_16x16x32_bf16 v[10:13], v[200:203], v[224:227], v[10:13]
	v_mfma_f32_16x16x32_bf16 v[6:9], v[184:187], v[232:235], v[6:9]
	v_mfma_f32_16x16x32_bf16 v[2:5], v[200:203], v[232:235], v[2:5]
	s_setprio 0
	s_barrier
	s_add_i32 s41, 0, 0x18000
	v_add_u32_e32 v142, s41, v145
	s_add_i32 s51, 0, 0x1c000
	ds_read_b128 v[130:133], v142
	ds_read_b128 v[168:171], v142 offset:1024
	ds_read_b128 v[172:175], v142 offset:2048
	ds_read_b128 v[176:179], v142 offset:3072
	v_add_u32_e32 v142, s51, v145
	ds_read_b128 v[180:183], v142
	ds_read_b128 v[184:187], v142 offset:1024
	ds_read_b128 v[194:197], v142 offset:2048
	ds_read_b128 v[200:203], v142 offset:3072
	s_add_u32 s10, s10, s20
	s_addc_u32 s11, s11, s21
	s_mov_b32 m0, s91
	v_lshl_add_u64 v[248:249], s[10:11], 0, v[134:135]
	ds_read_b128 v[204:207], v188 offset:32768
	ds_read_b128 v[208:211], v188 offset:33792
	ds_read_b128 v[212:215], v188 offset:34816
	ds_read_b128 v[216:219], v188 offset:35840
	ds_read_b128 v[220:223], v188 offset:36864
	ds_read_b128 v[224:227], v188 offset:37888
	ds_read_b128 v[228:231], v188 offset:38912
	ds_read_b128 v[232:235], v188 offset:39936
	global_load_lds_dwordx4 v[248:249], off
	v_lshl_add_u64 v[248:249], s[10:11], 0, v[138:139]
	s_mov_b32 m0, s92
	s_nop 0
	global_load_lds_dwordx4 v[248:249], off
	s_waitcnt vmcnt(8)
	s_waitcnt lgkmcnt(0)
	s_barrier
	s_setprio 1
	s_waitcnt lgkmcnt(0)
	v_mfma_f32_16x16x32_bf16 v[122:125], v[130:133], v[204:207], v[122:125]
	v_mfma_f32_16x16x32_bf16 v[126:129], v[172:175], v[204:207], v[126:129]
	v_mfma_f32_16x16x32_bf16 v[118:121], v[130:133], v[212:215], v[118:121]
	v_mfma_f32_16x16x32_bf16 v[114:117], v[172:175], v[212:215], v[114:117]
	v_mfma_f32_16x16x32_bf16 v[110:113], v[130:133], v[220:223], v[110:113]
	v_mfma_f32_16x16x32_bf16 v[106:109], v[172:175], v[220:223], v[106:109]
	v_mfma_f32_16x16x32_bf16 v[102:105], v[130:133], v[228:231], v[102:105]
	v_mfma_f32_16x16x32_bf16 v[98:101], v[172:175], v[228:231], v[98:101]
	v_mfma_f32_16x16x32_bf16 v[122:125], v[168:171], v[208:211], v[122:125]
	v_mfma_f32_16x16x32_bf16 v[126:129], v[176:179], v[208:211], v[126:129]
	v_mfma_f32_16x16x32_bf16 v[118:121], v[168:171], v[216:219], v[118:121]
	v_mfma_f32_16x16x32_bf16 v[114:117], v[176:179], v[216:219], v[114:117]
	v_mfma_f32_16x16x32_bf16 v[110:113], v[168:171], v[224:227], v[110:113]
	v_mfma_f32_16x16x32_bf16 v[106:109], v[176:179], v[224:227], v[106:109]
	v_mfma_f32_16x16x32_bf16 v[102:105], v[168:171], v[232:235], v[102:105]
	v_mfma_f32_16x16x32_bf16 v[98:101], v[176:179], v[232:235], v[98:101]
	s_setprio 0
	s_setprio 1
	v_mfma_f32_16x16x32_bf16 v[62:65], v[180:183], v[204:207], v[62:65]
	v_mfma_f32_16x16x32_bf16 v[58:61], v[194:197], v[204:207], v[58:61]
	v_mfma_f32_16x16x32_bf16 v[54:57], v[180:183], v[212:215], v[54:57]
	v_mfma_f32_16x16x32_bf16 v[50:53], v[194:197], v[212:215], v[50:53]
	v_mfma_f32_16x16x32_bf16 v[46:49], v[180:183], v[220:223], v[46:49]
	v_mfma_f32_16x16x32_bf16 v[42:45], v[194:197], v[220:223], v[42:45]
	v_mfma_f32_16x16x32_bf16 v[38:41], v[180:183], v[228:231], v[38:41]
	v_mfma_f32_16x16x32_bf16 v[34:37], v[194:197], v[228:231], v[34:37]
	v_mfma_f32_16x16x32_bf16 v[62:65], v[184:187], v[208:211], v[62:65]
	v_mfma_f32_16x16x32_bf16 v[58:61], v[200:203], v[208:211], v[58:61]
	v_mfma_f32_16x16x32_bf16 v[54:57], v[184:187], v[216:219], v[54:57]
	v_mfma_f32_16x16x32_bf16 v[50:53], v[200:203], v[216:219], v[50:53]
	v_mfma_f32_16x16x32_bf16 v[46:49], v[184:187], v[224:227], v[46:49]
	v_mfma_f32_16x16x32_bf16 v[42:45], v[200:203], v[224:227], v[42:45]
	v_mfma_f32_16x16x32_bf16 v[38:41], v[184:187], v[232:235], v[38:41]
	v_mfma_f32_16x16x32_bf16 v[34:37], v[200:203], v[232:235], v[34:37]
	s_setprio 0
	s_barrier
	s_add_i32 s10, s41, s90
	v_lshl_add_u64 v[236:237], v[236:237], 0, s[26:27]
	s_mov_b32 m0, s10
	ds_read_b128 v[204:207], v188 offset:49152
	ds_read_b128 v[208:211], v188 offset:50176
	ds_read_b128 v[212:215], v188 offset:51200
	ds_read_b128 v[216:219], v188 offset:52224
	ds_read_b128 v[220:223], v188 offset:53248
	ds_read_b128 v[224:227], v188 offset:54272
	ds_read_b128 v[228:231], v188 offset:55296
	ds_read_b128 v[232:235], v188 offset:56320
	global_load_lds_dwordx4 v[236:237], off
	v_lshl_add_u64 v[236:237], v[238:239], 0, s[26:27]
	s_add_i32 m0, s10, 0x2000
	s_add_i32 s10, s51, s90
	global_load_lds_dwordx4 v[236:237], off
	v_lshl_add_u64 v[236:237], v[240:241], 0, s[26:27]
	s_mov_b32 m0, s10
	s_nop 0
	global_load_lds_dwordx4 v[236:237], off
	v_lshl_add_u64 v[236:237], v[242:243], 0, s[26:27]
	s_add_i32 m0, s10, 0x2000
	s_nop 0
	global_load_lds_dwordx4 v[236:237], off
	v_lshl_add_u64 v[236:237], v[244:245], 0, s[26:27]
	s_mov_b32 m0, s97
	s_nop 0
	global_load_lds_dwordx4 v[236:237], off
	v_lshl_add_u64 v[236:237], v[246:247], 0, s[26:27]
	s_mov_b32 m0, s89
	s_nop 0
	global_load_lds_dwordx4 v[236:237], off
	s_waitcnt vmcnt(8)
	s_waitcnt lgkmcnt(0)
	s_barrier
	s_setprio 1
	s_waitcnt lgkmcnt(0)
	v_mfma_f32_16x16x32_bf16 v[94:97], v[130:133], v[204:207], v[94:97]
	v_mfma_f32_16x16x32_bf16 v[90:93], v[172:175], v[204:207], v[90:93]
	v_mfma_f32_16x16x32_bf16 v[86:89], v[130:133], v[212:215], v[86:89]
	v_mfma_f32_16x16x32_bf16 v[82:85], v[172:175], v[212:215], v[82:85]
	v_mfma_f32_16x16x32_bf16 v[78:81], v[130:133], v[220:223], v[78:81]
	v_mfma_f32_16x16x32_bf16 v[74:77], v[172:175], v[220:223], v[74:77]
	v_mfma_f32_16x16x32_bf16 v[70:73], v[130:133], v[228:231], v[70:73]
	v_mfma_f32_16x16x32_bf16 v[66:69], v[172:175], v[228:231], v[66:69]
	v_mfma_f32_16x16x32_bf16 v[94:97], v[168:171], v[208:211], v[94:97]
	v_mfma_f32_16x16x32_bf16 v[90:93], v[176:179], v[208:211], v[90:93]
	v_mfma_f32_16x16x32_bf16 v[86:89], v[168:171], v[216:219], v[86:89]
	v_mfma_f32_16x16x32_bf16 v[82:85], v[176:179], v[216:219], v[82:85]
	v_mfma_f32_16x16x32_bf16 v[78:81], v[168:171], v[224:227], v[78:81]
	v_mfma_f32_16x16x32_bf16 v[74:77], v[176:179], v[224:227], v[74:77]
	v_mfma_f32_16x16x32_bf16 v[70:73], v[168:171], v[232:235], v[70:73]
	v_mfma_f32_16x16x32_bf16 v[66:69], v[176:179], v[232:235], v[66:69]
	s_setprio 0
	s_setprio 1
	v_mfma_f32_16x16x32_bf16 v[30:33], v[180:183], v[204:207], v[30:33]
	v_mfma_f32_16x16x32_bf16 v[26:29], v[194:197], v[204:207], v[26:29]
	v_mfma_f32_16x16x32_bf16 v[22:25], v[180:183], v[212:215], v[22:25]
	v_mfma_f32_16x16x32_bf16 v[18:21], v[194:197], v[212:215], v[18:21]
	v_mfma_f32_16x16x32_bf16 v[14:17], v[180:183], v[220:223], v[14:17]
	v_mfma_f32_16x16x32_bf16 v[10:13], v[194:197], v[220:223], v[10:13]
	v_mfma_f32_16x16x32_bf16 v[6:9], v[180:183], v[228:231], v[6:9]
	v_mfma_f32_16x16x32_bf16 v[2:5], v[194:197], v[228:231], v[2:5]
	v_mfma_f32_16x16x32_bf16 v[30:33], v[184:187], v[208:211], v[30:33]
	v_mfma_f32_16x16x32_bf16 v[26:29], v[200:203], v[208:211], v[26:29]
	v_mfma_f32_16x16x32_bf16 v[22:25], v[184:187], v[216:219], v[22:25]
	v_mfma_f32_16x16x32_bf16 v[18:21], v[200:203], v[216:219], v[18:21]
	v_mfma_f32_16x16x32_bf16 v[14:17], v[184:187], v[224:227], v[14:17]
	v_mfma_f32_16x16x32_bf16 v[10:13], v[200:203], v[224:227], v[10:13]
	v_mfma_f32_16x16x32_bf16 v[6:9], v[184:187], v[232:235], v[6:9]
	v_mfma_f32_16x16x32_bf16 v[2:5], v[200:203], v[232:235], v[2:5]
	s_setprio 0
	s_barrier
	s_add_u32 s8, s8, 0x100
	s_addc_u32 s9, s9, 0
	s_add_u32 s14, s14, 0x100
	s_addc_u32 s15, s15, 0
	s_cmp_ge_i32 s40, s74
	s_mov_b32 s10, s40
	s_cbranch_scc0 .LBB0_353
	s_getpc_b64 s[98:99]
	s_mov_b32 m0, 0x22800
	v_lshlrev_b32_e32 v232, 7, v0
	global_load_lds_dword v232, s[98:99]

.LBB0_867:
	s_waitcnt lgkmcnt(0)
	ds_read_b128 v[130:133], v189
	ds_read_b128 v[168:171], v189 offset:1024
	ds_read_b128 v[172:175], v189 offset:2048
	ds_read_b128 v[176:179], v189 offset:3072
	ds_read_b128 v[180:183], v190
	ds_read_b128 v[184:187], v190 offset:1024
	ds_read_b128 v[194:197], v190 offset:2048
	ds_read_b128 v[200:203], v190 offset:3072
	s_add_i32 s45, s10, 2
	s_add_u32 s55, s8, 0x80
	s_addc_u32 s11, s9, 0
	s_cmp_eq_u32 s87, s10
	s_cselect_b32 s10, s12, s55
	s_cselect_b32 s11, s3, s11
	s_cselect_b32 s65, s13, s44
	s_cselect_b32 s64, s14, s15
	v_lshl_add_u64 v[236:237], s[8:9], 0, v[164:165]
	s_add_i32 m0, s27, 0xc000
	ds_read_b128 v[204:207], v188
	ds_read_b128 v[208:211], v188 offset:1024
	ds_read_b128 v[212:215], v188 offset:2048
	ds_read_b128 v[216:219], v188 offset:3072
	ds_read_b128 v[220:223], v188 offset:4096
	ds_read_b128 v[224:227], v188 offset:5120
	ds_read_b128 v[228:231], v188 offset:6144
	ds_read_b128 v[232:235], v188 offset:7168
	global_load_lds_dwordx4 v[236:237], off
	v_lshl_add_u64 v[236:237], s[8:9], 0, v[166:167]
	s_add_i32 m0, s27, 0xe000
	s_nop 0
	global_load_lds_dwordx4 v[236:237], off
	s_waitcnt vmcnt(8)
	s_waitcnt lgkmcnt(0)
	s_barrier
	s_setprio 1
	s_waitcnt lgkmcnt(0)
	v_mfma_f32_16x16x32_bf16 v[122:125], v[130:133], v[204:207], v[122:125]
	v_mfma_f32_16x16x32_bf16 v[126:129], v[172:175], v[204:207], v[126:129]
	v_mfma_f32_16x16x32_bf16 v[118:121], v[130:133], v[212:215], v[118:121]
	v_mfma_f32_16x16x32_bf16 v[114:117], v[172:175], v[212:215], v[114:117]
	v_mfma_f32_16x16x32_bf16 v[110:113], v[130:133], v[220:223], v[110:113]
	v_mfma_f32_16x16x32_bf16 v[106:109], v[172:175], v[220:223], v[106:109]
	v_mfma_f32_16x16x32_bf16 v[102:105], v[130:133], v[228:231], v[102:105]
	v_mfma_f32_16x16x32_bf16 v[98:101], v[172:175], v[228:231], v[98:101]
	v_mfma_f32_16x16x32_bf16 v[122:125], v[168:171], v[208:211], v[122:125]
	v_mfma_f32_16x16x32_bf16 v[126:129], v[176:179], v[208:211], v[126:129]
	v_mfma_f32_16x16x32_bf16 v[118:121], v[168:171], v[216:219], v[118:121]
	v_mfma_f32_16x16x32_bf16 v[114:117], v[176:179], v[216:219], v[114:117]
	v_mfma_f32_16x16x32_bf16 v[110:113], v[168:171], v[224:227], v[110:113]
	v_mfma_f32_16x16x32_bf16 v[106:109], v[176:179], v[224:227], v[106:109]
	v_mfma_f32_16x16x32_bf16 v[102:105], v[168:171], v[232:235], v[102:105]
	v_mfma_f32_16x16x32_bf16 v[98:101], v[176:179], v[232:235], v[98:101]
	s_setprio 0
	s_setprio 1
	v_mfma_f32_16x16x32_bf16 v[62:65], v[180:183], v[204:207], v[62:65]
	v_mfma_f32_16x16x32_bf16 v[58:61], v[194:197], v[204:207], v[58:61]
	v_mfma_f32_16x16x32_bf16 v[54:57], v[180:183], v[212:215], v[54:57]
	v_mfma_f32_16x16x32_bf16 v[50:53], v[194:197], v[212:215], v[50:53]
	v_mfma_f32_16x16x32_bf16 v[46:49], v[180:183], v[220:223], v[46:49]
	v_mfma_f32_16x16x32_bf16 v[42:45], v[194:197], v[220:223], v[42:45]
	v_mfma_f32_16x16x32_bf16 v[38:41], v[180:183], v[228:231], v[38:41]
	v_mfma_f32_16x16x32_bf16 v[34:37], v[194:197], v[228:231], v[34:37]
	v_mfma_f32_16x16x32_bf16 v[62:65], v[184:187], v[208:211], v[62:65]
	v_mfma_f32_16x16x32_bf16 v[58:61], v[200:203], v[208:211], v[58:61]
	v_mfma_f32_16x16x32_bf16 v[54:57], v[184:187], v[216:219], v[54:57]
	v_mfma_f32_16x16x32_bf16 v[50:53], v[200:203], v[216:219], v[50:53]
	v_mfma_f32_16x16x32_bf16 v[46:49], v[184:187], v[224:227], v[46:49]
	v_mfma_f32_16x16x32_bf16 v[42:45], v[200:203], v[224:227], v[42:45]
	v_mfma_f32_16x16x32_bf16 v[38:41], v[184:187], v[232:235], v[38:41]
	v_mfma_f32_16x16x32_bf16 v[34:37], v[200:203], v[232:235], v[34:37]
	s_setprio 0
	s_barrier
	s_add_i32 s55, s16, s93
	v_lshl_add_u64 v[236:237], s[64:65], 0, v[136:137]
	s_mov_b32 m0, s55
	ds_read_b128 v[204:207], v188 offset:16384
	ds_read_b128 v[208:211], v188 offset:17408
	ds_read_b128 v[212:215], v188 offset:18432
	ds_read_b128 v[216:219], v188 offset:19456
	ds_read_b128 v[220:223], v188 offset:20480
	ds_read_b128 v[224:227], v188 offset:21504
	ds_read_b128 v[228:231], v188 offset:22528
	ds_read_b128 v[232:235], v188 offset:23552
	global_load_lds_dwordx4 v[236:237], off
	s_add_i32 m0, s55, 0x2000
	v_lshl_add_u64 v[238:239], s[64:65], 0, v[140:141]
	s_add_u32 s64, s64, s24
	s_addc_u32 s65, s65, s25
	s_add_i32 s55, s19, s93
	global_load_lds_dwordx4 v[238:239], off
	v_lshl_add_u64 v[240:241], s[64:65], 0, v[136:137]
	s_mov_b32 m0, s55
	v_lshl_add_u64 v[242:243], s[64:65], 0, v[140:141]
	global_load_lds_dwordx4 v[240:241], off
	s_add_i32 m0, s55, 0x2000
	v_lshl_add_u64 v[244:245], s[10:11], 0, v[134:135]
	global_load_lds_dwordx4 v[242:243], off
	s_mov_b32 m0, s27
	v_lshl_add_u64 v[246:247], s[10:11], 0, v[138:139]
	global_load_lds_dwordx4 v[244:245], off
	s_mov_b32 m0, s35
	s_nop 0
	global_load_lds_dwordx4 v[246:247], off
	s_waitcnt vmcnt(8)
	s_waitcnt lgkmcnt(0)
	s_barrier
	s_setprio 1
	s_waitcnt lgkmcnt(0)
	v_mfma_f32_16x16x32_bf16 v[94:97], v[130:133], v[204:207], v[94:97]
	v_mfma_f32_16x16x32_bf16 v[90:93], v[172:175], v[204:207], v[90:93]
	v_mfma_f32_16x16x32_bf16 v[86:89], v[130:133], v[212:215], v[86:89]
	v_mfma_f32_16x16x32_bf16 v[82:85], v[172:175], v[212:215], v[82:85]
	v_mfma_f32_16x16x32_bf16 v[78:81], v[130:133], v[220:223], v[78:81]
	v_mfma_f32_16x16x32_bf16 v[74:77], v[172:175], v[220:223], v[74:77]
	v_mfma_f32_16x16x32_bf16 v[70:73], v[130:133], v[228:231], v[70:73]
	v_mfma_f32_16x16x32_bf16 v[66:69], v[172:175], v[228:231], v[66:69]
	v_mfma_f32_16x16x32_bf16 v[94:97], v[168:171], v[208:211], v[94:97]
	v_mfma_f32_16x16x32_bf16 v[90:93], v[176:179], v[208:211], v[90:93]
	v_mfma_f32_16x16x32_bf16 v[86:89], v[168:171], v[216:219], v[86:89]
	v_mfma_f32_16x16x32_bf16 v[82:85], v[176:179], v[216:219], v[82:85]
	v_mfma_f32_16x16x32_bf16 v[78:81], v[168:171], v[224:227], v[78:81]
	v_mfma_f32_16x16x32_bf16 v[74:77], v[176:179], v[224:227], v[74:77]
	v_mfma_f32_16x16x32_bf16 v[70:73], v[168:171], v[232:235], v[70:73]
	v_mfma_f32_16x16x32_bf16 v[66:69], v[176:179], v[232:235], v[66:69]
	s_setprio 0
	s_setprio 1
	v_mfma_f32_16x16x32_bf16 v[30:33], v[180:183], v[204:207], v[30:33]
	v_mfma_f32_16x16x32_bf16 v[26:29], v[194:197], v[204:207], v[26:29]
	v_mfma_f32_16x16x32_bf16 v[22:25], v[180:183], v[212:215], v[22:25]
	v_mfma_f32_16x16x32_bf16 v[18:21], v[194:197], v[212:215], v[18:21]
	v_mfma_f32_16x16x32_bf16 v[14:17], v[180:183], v[220:223], v[14:17]
	v_mfma_f32_16x16x32_bf16 v[10:13], v[194:197], v[220:223], v[10:13]
	v_mfma_f32_16x16x32_bf16 v[6:9], v[180:183], v[228:231], v[6:9]
	v_mfma_f32_16x16x32_bf16 v[2:5], v[194:197], v[228:231], v[2:5]
	v_mfma_f32_16x16x32_bf16 v[30:33], v[184:187], v[208:211], v[30:33]
	v_mfma_f32_16x16x32_bf16 v[26:29], v[200:203], v[208:211], v[26:29]
	v_mfma_f32_16x16x32_bf16 v[22:25], v[184:187], v[216:219], v[22:25]
	v_mfma_f32_16x16x32_bf16 v[18:21], v[200:203], v[216:219], v[18:21]
	v_mfma_f32_16x16x32_bf16 v[14:17], v[184:187], v[224:227], v[14:17]
	v_mfma_f32_16x16x32_bf16 v[10:13], v[200:203], v[224:227], v[10:13]
	v_mfma_f32_16x16x32_bf16 v[6:9], v[184:187], v[232:235], v[6:9]
	v_mfma_f32_16x16x32_bf16 v[2:5], v[200:203], v[232:235], v[2:5]
	s_setprio 0
	s_barrier
	s_add_i32 s55, 0, 0x18000
	v_add_u32_e32 v142, s55, v145
	s_add_i32 s57, 0, 0x1c000
	ds_read_b128 v[130:133], v142
	ds_read_b128 v[168:171], v142 offset:1024
	ds_read_b128 v[172:175], v142 offset:2048
	ds_read_b128 v[176:179], v142 offset:3072
	v_add_u32_e32 v142, s57, v145
	ds_read_b128 v[180:183], v142
	ds_read_b128 v[184:187], v142 offset:1024
	ds_read_b128 v[194:197], v142 offset:2048
	ds_read_b128 v[200:203], v142 offset:3072
	s_add_u32 s10, s10, s24
	s_addc_u32 s11, s11, s25
	s_mov_b32 m0, s94
	v_lshl_add_u64 v[248:249], s[10:11], 0, v[134:135]
	ds_read_b128 v[204:207], v188 offset:32768
	ds_read_b128 v[208:211], v188 offset:33792
	ds_read_b128 v[212:215], v188 offset:34816
	ds_read_b128 v[216:219], v188 offset:35840
	ds_read_b128 v[220:223], v188 offset:36864
	ds_read_b128 v[224:227], v188 offset:37888
	ds_read_b128 v[228:231], v188 offset:38912
	ds_read_b128 v[232:235], v188 offset:39936
	global_load_lds_dwordx4 v[248:249], off
	v_lshl_add_u64 v[248:249], s[10:11], 0, v[138:139]
	s_mov_b32 m0, s95
	s_nop 0
	global_load_lds_dwordx4 v[248:249], off
	s_waitcnt vmcnt(8)
	s_waitcnt lgkmcnt(0)
	s_barrier
	s_setprio 1
	s_waitcnt lgkmcnt(0)
	v_mfma_f32_16x16x32_bf16 v[122:125], v[130:133], v[204:207], v[122:125]
	v_mfma_f32_16x16x32_bf16 v[126:129], v[172:175], v[204:207], v[126:129]
	v_mfma_f32_16x16x32_bf16 v[118:121], v[130:133], v[212:215], v[118:121]
	v_mfma_f32_16x16x32_bf16 v[114:117], v[172:175], v[212:215], v[114:117]
	v_mfma_f32_16x16x32_bf16 v[110:113], v[130:133], v[220:223], v[110:113]
	v_mfma_f32_16x16x32_bf16 v[106:109], v[172:175], v[220:223], v[106:109]
	v_mfma_f32_16x16x32_bf16 v[102:105], v[130:133], v[228:231], v[102:105]
	v_mfma_f32_16x16x32_bf16 v[98:101], v[172:175], v[228:231], v[98:101]
	v_mfma_f32_16x16x32_bf16 v[122:125], v[168:171], v[208:211], v[122:125]
	v_mfma_f32_16x16x32_bf16 v[126:129], v[176:179], v[208:211], v[126:129]
	v_mfma_f32_16x16x32_bf16 v[118:121], v[168:171], v[216:219], v[118:121]
	v_mfma_f32_16x16x32_bf16 v[114:117], v[176:179], v[216:219], v[114:117]
	v_mfma_f32_16x16x32_bf16 v[110:113], v[168:171], v[224:227], v[110:113]
	v_mfma_f32_16x16x32_bf16 v[106:109], v[176:179], v[224:227], v[106:109]
	v_mfma_f32_16x16x32_bf16 v[102:105], v[168:171], v[232:235], v[102:105]
	v_mfma_f32_16x16x32_bf16 v[98:101], v[176:179], v[232:235], v[98:101]
	s_setprio 0
	s_setprio 1
	v_mfma_f32_16x16x32_bf16 v[62:65], v[180:183], v[204:207], v[62:65]
	v_mfma_f32_16x16x32_bf16 v[58:61], v[194:197], v[204:207], v[58:61]
	v_mfma_f32_16x16x32_bf16 v[54:57], v[180:183], v[212:215], v[54:57]
	v_mfma_f32_16x16x32_bf16 v[50:53], v[194:197], v[212:215], v[50:53]
	v_mfma_f32_16x16x32_bf16 v[46:49], v[180:183], v[220:223], v[46:49]
	v_mfma_f32_16x16x32_bf16 v[42:45], v[194:197], v[220:223], v[42:45]
	v_mfma_f32_16x16x32_bf16 v[38:41], v[180:183], v[228:231], v[38:41]
	v_mfma_f32_16x16x32_bf16 v[34:37], v[194:197], v[228:231], v[34:37]
	v_mfma_f32_16x16x32_bf16 v[62:65], v[184:187], v[208:211], v[62:65]
	v_mfma_f32_16x16x32_bf16 v[58:61], v[200:203], v[208:211], v[58:61]
	v_mfma_f32_16x16x32_bf16 v[54:57], v[184:187], v[216:219], v[54:57]
	v_mfma_f32_16x16x32_bf16 v[50:53], v[200:203], v[216:219], v[50:53]
	v_mfma_f32_16x16x32_bf16 v[46:49], v[184:187], v[224:227], v[46:49]
	v_mfma_f32_16x16x32_bf16 v[42:45], v[200:203], v[224:227], v[42:45]
	v_mfma_f32_16x16x32_bf16 v[38:41], v[184:187], v[232:235], v[38:41]
	v_mfma_f32_16x16x32_bf16 v[34:37], v[200:203], v[232:235], v[34:37]
	s_setprio 0
	s_barrier
	s_add_i32 s10, s55, s93
	v_lshl_add_u64 v[236:237], v[236:237], 0, s[30:31]
	s_mov_b32 m0, s10
	ds_read_b128 v[204:207], v188 offset:49152
	ds_read_b128 v[208:211], v188 offset:50176
	ds_read_b128 v[212:215], v188 offset:51200
	ds_read_b128 v[216:219], v188 offset:52224
	ds_read_b128 v[220:223], v188 offset:53248
	ds_read_b128 v[224:227], v188 offset:54272
	ds_read_b128 v[228:231], v188 offset:55296
	ds_read_b128 v[232:235], v188 offset:56320
	global_load_lds_dwordx4 v[236:237], off
	v_lshl_add_u64 v[236:237], v[238:239], 0, s[30:31]
	s_add_i32 m0, s10, 0x2000
	s_add_i32 s10, s57, s93
	global_load_lds_dwordx4 v[236:237], off
	v_lshl_add_u64 v[236:237], v[240:241], 0, s[30:31]
	s_mov_b32 m0, s10
	s_nop 0
	global_load_lds_dwordx4 v[236:237], off
	v_lshl_add_u64 v[236:237], v[242:243], 0, s[30:31]
	s_add_i32 m0, s10, 0x2000
	s_nop 0
	global_load_lds_dwordx4 v[236:237], off
	v_lshl_add_u64 v[236:237], v[244:245], 0, s[30:31]
	s_mov_b32 m0, s74
	s_nop 0
	global_load_lds_dwordx4 v[236:237], off
	v_lshl_add_u64 v[236:237], v[246:247], 0, s[30:31]
	s_mov_b32 m0, s75
	s_nop 0
	global_load_lds_dwordx4 v[236:237], off
	s_waitcnt vmcnt(8)
	s_waitcnt lgkmcnt(0)
	s_barrier
	s_setprio 1
	s_waitcnt lgkmcnt(0)
	v_mfma_f32_16x16x32_bf16 v[94:97], v[130:133], v[204:207], v[94:97]
	v_mfma_f32_16x16x32_bf16 v[90:93], v[172:175], v[204:207], v[90:93]
	v_mfma_f32_16x16x32_bf16 v[86:89], v[130:133], v[212:215], v[86:89]
	v_mfma_f32_16x16x32_bf16 v[82:85], v[172:175], v[212:215], v[82:85]
	v_mfma_f32_16x16x32_bf16 v[78:81], v[130:133], v[220:223], v[78:81]
	v_mfma_f32_16x16x32_bf16 v[74:77], v[172:175], v[220:223], v[74:77]
	v_mfma_f32_16x16x32_bf16 v[70:73], v[130:133], v[228:231], v[70:73]
	v_mfma_f32_16x16x32_bf16 v[66:69], v[172:175], v[228:231], v[66:69]
	v_mfma_f32_16x16x32_bf16 v[94:97], v[168:171], v[208:211], v[94:97]
	v_mfma_f32_16x16x32_bf16 v[90:93], v[176:179], v[208:211], v[90:93]
	v_mfma_f32_16x16x32_bf16 v[86:89], v[168:171], v[216:219], v[86:89]
	v_mfma_f32_16x16x32_bf16 v[82:85], v[176:179], v[216:219], v[82:85]
	v_mfma_f32_16x16x32_bf16 v[78:81], v[168:171], v[224:227], v[78:81]
	v_mfma_f32_16x16x32_bf16 v[74:77], v[176:179], v[224:227], v[74:77]
	v_mfma_f32_16x16x32_bf16 v[70:73], v[168:171], v[232:235], v[70:73]
	v_mfma_f32_16x16x32_bf16 v[66:69], v[176:179], v[232:235], v[66:69]
	s_setprio 0
	s_setprio 1
	v_mfma_f32_16x16x32_bf16 v[30:33], v[180:183], v[204:207], v[30:33]
	v_mfma_f32_16x16x32_bf16 v[26:29], v[194:197], v[204:207], v[26:29]
	v_mfma_f32_16x16x32_bf16 v[22:25], v[180:183], v[212:215], v[22:25]
	v_mfma_f32_16x16x32_bf16 v[18:21], v[194:197], v[212:215], v[18:21]
	v_mfma_f32_16x16x32_bf16 v[14:17], v[180:183], v[220:223], v[14:17]
	v_mfma_f32_16x16x32_bf16 v[10:13], v[194:197], v[220:223], v[10:13]
	v_mfma_f32_16x16x32_bf16 v[6:9], v[180:183], v[228:231], v[6:9]
	v_mfma_f32_16x16x32_bf16 v[2:5], v[194:197], v[228:231], v[2:5]
	v_mfma_f32_16x16x32_bf16 v[30:33], v[184:187], v[208:211], v[30:33]
	v_mfma_f32_16x16x32_bf16 v[26:29], v[200:203], v[208:211], v[26:29]
	v_mfma_f32_16x16x32_bf16 v[22:25], v[184:187], v[216:219], v[22:25]
	v_mfma_f32_16x16x32_bf16 v[18:21], v[200:203], v[216:219], v[18:21]
	v_mfma_f32_16x16x32_bf16 v[14:17], v[184:187], v[224:227], v[14:17]
	v_mfma_f32_16x16x32_bf16 v[10:13], v[200:203], v[224:227], v[10:13]
	v_mfma_f32_16x16x32_bf16 v[6:9], v[184:187], v[232:235], v[6:9]
	v_mfma_f32_16x16x32_bf16 v[2:5], v[200:203], v[232:235], v[2:5]
	s_setprio 0
	s_barrier
	s_add_u32 s8, s8, 0x100
	s_addc_u32 s9, s9, 0
	s_add_u32 s15, s15, 0x100
	s_addc_u32 s44, s44, 0
	s_cmp_ge_i32 s45, s22
	s_mov_b32 s10, s45
	s_cbranch_scc0 .LBB0_867
	s_getpc_b64 s[98:99]
	s_mov_b32 m0, 0x22800
	v_lshlrev_b32_e32 v232, 7, v0
	global_load_lds_dword v232, s[98:99]

.LBB0_1337:
	ds_read_b128 v[150:153], v172
	ds_read_b128 v[154:157], v172 offset:1024
	ds_read_b128 v[158:161], v172 offset:2048
	ds_read_b128 v[162:165], v172 offset:3072
	ds_read_b128 v[180:183], v173
	ds_read_b128 v[184:187], v173 offset:1024
	ds_read_b128 v[188:191], v173 offset:2048
	ds_read_b128 v[192:195], v173 offset:3072
	s_add_i32 s53, s10, 2
	s_add_u32 s54, s8, 0x80
	s_addc_u32 s11, s9, 0
	s_cmp_eq_u32 s64, s10
	s_cselect_b32 s10, s21, s54
	s_cselect_b32 s11, s2, s11
	s_cselect_b32 s55, s41, s52
	s_cselect_b32 s54, s50, s51
	v_lshl_add_u64 v[196:197], s[8:9], 0, v[146:147]
	s_add_i32 m0, s18, 0xc000
	ds_read_b128 v[200:203], v174
	ds_read_b128 v[204:207], v174 offset:1024
	ds_read_b128 v[208:211], v174 offset:2048
	ds_read_b128 v[212:215], v174 offset:3072
	ds_read_b128 v[216:219], v174 offset:4096
	ds_read_b128 v[220:223], v174 offset:5120
	ds_read_b128 v[224:227], v174 offset:6144
	ds_read_b128 v[228:231], v174 offset:7168
	global_load_lds_dwordx4 v[196:197], off
	v_lshl_add_u64 v[196:197], s[8:9], 0, v[148:149]
	s_add_i32 m0, s18, 0xe000
	s_nop 0
	global_load_lds_dwordx4 v[196:197], off
	s_waitcnt vmcnt(8)
	s_waitcnt lgkmcnt(0)
	s_barrier
	s_setprio 1
	s_waitcnt lgkmcnt(0)
	v_mfma_f32_16x16x32_bf16 v[122:125], v[150:153], v[200:203], v[122:125]
	v_mfma_f32_16x16x32_bf16 v[126:129], v[158:161], v[200:203], v[126:129]
	v_mfma_f32_16x16x32_bf16 v[118:121], v[150:153], v[208:211], v[118:121]
	v_mfma_f32_16x16x32_bf16 v[114:117], v[158:161], v[208:211], v[114:117]
	v_mfma_f32_16x16x32_bf16 v[110:113], v[150:153], v[216:219], v[110:113]
	v_mfma_f32_16x16x32_bf16 v[106:109], v[158:161], v[216:219], v[106:109]
	v_mfma_f32_16x16x32_bf16 v[102:105], v[150:153], v[224:227], v[102:105]
	v_mfma_f32_16x16x32_bf16 v[98:101], v[158:161], v[224:227], v[98:101]
	v_mfma_f32_16x16x32_bf16 v[122:125], v[154:157], v[204:207], v[122:125]
	v_mfma_f32_16x16x32_bf16 v[126:129], v[162:165], v[204:207], v[126:129]
	v_mfma_f32_16x16x32_bf16 v[118:121], v[154:157], v[212:215], v[118:121]
	v_mfma_f32_16x16x32_bf16 v[114:117], v[162:165], v[212:215], v[114:117]
	v_mfma_f32_16x16x32_bf16 v[110:113], v[154:157], v[220:223], v[110:113]
	v_mfma_f32_16x16x32_bf16 v[106:109], v[162:165], v[220:223], v[106:109]
	v_mfma_f32_16x16x32_bf16 v[102:105], v[154:157], v[228:231], v[102:105]
	v_mfma_f32_16x16x32_bf16 v[98:101], v[162:165], v[228:231], v[98:101]
	s_setprio 0
	s_setprio 1
	v_mfma_f32_16x16x32_bf16 v[62:65], v[180:183], v[200:203], v[62:65]
	v_mfma_f32_16x16x32_bf16 v[58:61], v[188:191], v[200:203], v[58:61]
	v_mfma_f32_16x16x32_bf16 v[54:57], v[180:183], v[208:211], v[54:57]
	v_mfma_f32_16x16x32_bf16 v[50:53], v[188:191], v[208:211], v[50:53]
	v_mfma_f32_16x16x32_bf16 v[46:49], v[180:183], v[216:219], v[46:49]
	v_mfma_f32_16x16x32_bf16 v[42:45], v[188:191], v[216:219], v[42:45]
	v_mfma_f32_16x16x32_bf16 v[38:41], v[180:183], v[224:227], v[38:41]
	v_mfma_f32_16x16x32_bf16 v[34:37], v[188:191], v[224:227], v[34:37]
	v_mfma_f32_16x16x32_bf16 v[62:65], v[184:187], v[204:207], v[62:65]
	v_mfma_f32_16x16x32_bf16 v[58:61], v[192:195], v[204:207], v[58:61]
	v_mfma_f32_16x16x32_bf16 v[54:57], v[184:187], v[212:215], v[54:57]
	v_mfma_f32_16x16x32_bf16 v[50:53], v[192:195], v[212:215], v[50:53]
	v_mfma_f32_16x16x32_bf16 v[46:49], v[184:187], v[220:223], v[46:49]
	v_mfma_f32_16x16x32_bf16 v[42:45], v[192:195], v[220:223], v[42:45]
	v_mfma_f32_16x16x32_bf16 v[38:41], v[184:187], v[228:231], v[38:41]
	v_mfma_f32_16x16x32_bf16 v[34:37], v[192:195], v[228:231], v[34:37]
	s_setprio 0
	s_barrier
	s_add_i32 s84, s68, s16
	v_lshl_add_u64 v[196:197], s[54:55], 0, v[132:133]
	s_mov_b32 m0, s84
	ds_read_b128 v[200:203], v174 offset:16384
	ds_read_b128 v[204:207], v174 offset:17408
	ds_read_b128 v[208:211], v174 offset:18432
	ds_read_b128 v[212:215], v174 offset:19456
	ds_read_b128 v[216:219], v174 offset:20480
	ds_read_b128 v[220:223], v174 offset:21504
	ds_read_b128 v[224:227], v174 offset:22528
	ds_read_b128 v[228:231], v174 offset:23552
	global_load_lds_dwordx4 v[196:197], off
	s_add_i32 m0, s84, 0x2000
	v_lshl_add_u64 v[232:233], s[54:55], 0, v[136:137]
	s_add_u32 s54, s54, s12
	s_addc_u32 s55, s55, s13
	s_add_i32 s84, s69, s16
	global_load_lds_dwordx4 v[232:233], off
	v_lshl_add_u64 v[234:235], s[54:55], 0, v[132:133]
	s_mov_b32 m0, s84
	v_lshl_add_u64 v[236:237], s[54:55], 0, v[136:137]
	global_load_lds_dwordx4 v[234:235], off
	s_add_i32 m0, s84, 0x2000
	v_lshl_add_u64 v[238:239], s[10:11], 0, v[130:131]
	global_load_lds_dwordx4 v[236:237], off
	s_mov_b32 m0, s18
	v_lshl_add_u64 v[240:241], s[10:11], 0, v[134:135]
	global_load_lds_dwordx4 v[238:239], off
	s_mov_b32 m0, s19
	s_nop 0
	global_load_lds_dwordx4 v[240:241], off
	s_waitcnt vmcnt(8)
	s_waitcnt lgkmcnt(0)
	s_barrier
	s_setprio 1
	s_waitcnt lgkmcnt(0)
	v_mfma_f32_16x16x32_bf16 v[94:97], v[150:153], v[200:203], v[94:97]
	v_mfma_f32_16x16x32_bf16 v[90:93], v[158:161], v[200:203], v[90:93]
	v_mfma_f32_16x16x32_bf16 v[86:89], v[150:153], v[208:211], v[86:89]
	v_mfma_f32_16x16x32_bf16 v[82:85], v[158:161], v[208:211], v[82:85]
	v_mfma_f32_16x16x32_bf16 v[78:81], v[150:153], v[216:219], v[78:81]
	v_mfma_f32_16x16x32_bf16 v[74:77], v[158:161], v[216:219], v[74:77]
	v_mfma_f32_16x16x32_bf16 v[70:73], v[150:153], v[224:227], v[70:73]
	v_mfma_f32_16x16x32_bf16 v[66:69], v[158:161], v[224:227], v[66:69]
	v_mfma_f32_16x16x32_bf16 v[94:97], v[154:157], v[204:207], v[94:97]
	v_mfma_f32_16x16x32_bf16 v[90:93], v[162:165], v[204:207], v[90:93]
	v_mfma_f32_16x16x32_bf16 v[86:89], v[154:157], v[212:215], v[86:89]
	v_mfma_f32_16x16x32_bf16 v[82:85], v[162:165], v[212:215], v[82:85]
	v_mfma_f32_16x16x32_bf16 v[78:81], v[154:157], v[220:223], v[78:81]
	v_mfma_f32_16x16x32_bf16 v[74:77], v[162:165], v[220:223], v[74:77]
	v_mfma_f32_16x16x32_bf16 v[70:73], v[154:157], v[228:231], v[70:73]
	v_mfma_f32_16x16x32_bf16 v[66:69], v[162:165], v[228:231], v[66:69]
	s_setprio 0
	s_setprio 1
	v_mfma_f32_16x16x32_bf16 v[30:33], v[180:183], v[200:203], v[30:33]
	v_mfma_f32_16x16x32_bf16 v[26:29], v[188:191], v[200:203], v[26:29]
	v_mfma_f32_16x16x32_bf16 v[22:25], v[180:183], v[208:211], v[22:25]
	v_mfma_f32_16x16x32_bf16 v[18:21], v[188:191], v[208:211], v[18:21]
	v_mfma_f32_16x16x32_bf16 v[14:17], v[180:183], v[216:219], v[14:17]
	v_mfma_f32_16x16x32_bf16 v[10:13], v[188:191], v[216:219], v[10:13]
	v_mfma_f32_16x16x32_bf16 v[6:9], v[180:183], v[224:227], v[6:9]
	v_mfma_f32_16x16x32_bf16 v[2:5], v[188:191], v[224:227], v[2:5]
	v_mfma_f32_16x16x32_bf16 v[30:33], v[184:187], v[204:207], v[30:33]
	v_mfma_f32_16x16x32_bf16 v[26:29], v[192:195], v[204:207], v[26:29]
	v_mfma_f32_16x16x32_bf16 v[22:25], v[184:187], v[212:215], v[22:25]
	v_mfma_f32_16x16x32_bf16 v[18:21], v[192:195], v[212:215], v[18:21]
	v_mfma_f32_16x16x32_bf16 v[14:17], v[184:187], v[220:223], v[14:17]
	v_mfma_f32_16x16x32_bf16 v[10:13], v[192:195], v[220:223], v[10:13]
	v_mfma_f32_16x16x32_bf16 v[6:9], v[184:187], v[228:231], v[6:9]
	v_mfma_f32_16x16x32_bf16 v[2:5], v[192:195], v[228:231], v[2:5]
	s_setprio 0
	s_barrier
	s_add_i32 s54, 0, 0x18000
	v_add_u32_e32 v138, s54, v166
	s_add_i32 s55, 0, 0x1c000
	ds_read_b128 v[150:153], v138
	ds_read_b128 v[154:157], v138 offset:1024
	ds_read_b128 v[158:161], v138 offset:2048
	ds_read_b128 v[162:165], v138 offset:3072
	v_add_u32_e32 v138, s55, v166
	ds_read_b128 v[180:183], v138
	ds_read_b128 v[184:187], v138 offset:1024
	ds_read_b128 v[188:191], v138 offset:2048
	ds_read_b128 v[192:195], v138 offset:3072
	s_add_u32 s10, s10, s12
	s_addc_u32 s11, s11, s13
	s_mov_b32 m0, s33
	v_lshl_add_u64 v[242:243], s[10:11], 0, v[130:131]
	ds_read_b128 v[200:203], v174 offset:32768
	ds_read_b128 v[204:207], v174 offset:33792
	ds_read_b128 v[208:211], v174 offset:34816
	ds_read_b128 v[212:215], v174 offset:35840
	ds_read_b128 v[216:219], v174 offset:36864
	ds_read_b128 v[220:223], v174 offset:37888
	ds_read_b128 v[224:227], v174 offset:38912
	ds_read_b128 v[228:231], v174 offset:39936
	global_load_lds_dwordx4 v[242:243], off
	v_lshl_add_u64 v[242:243], s[10:11], 0, v[134:135]
	s_mov_b32 m0, s39
	s_nop 0
	global_load_lds_dwordx4 v[242:243], off
	s_waitcnt vmcnt(8)
	s_waitcnt lgkmcnt(0)
	s_barrier
	s_setprio 1
	s_waitcnt lgkmcnt(0)
	v_mfma_f32_16x16x32_bf16 v[122:125], v[150:153], v[200:203], v[122:125]
	v_mfma_f32_16x16x32_bf16 v[126:129], v[158:161], v[200:203], v[126:129]
	v_mfma_f32_16x16x32_bf16 v[118:121], v[150:153], v[208:211], v[118:121]
	v_mfma_f32_16x16x32_bf16 v[114:117], v[158:161], v[208:211], v[114:117]
	v_mfma_f32_16x16x32_bf16 v[110:113], v[150:153], v[216:219], v[110:113]
	v_mfma_f32_16x16x32_bf16 v[106:109], v[158:161], v[216:219], v[106:109]
	v_mfma_f32_16x16x32_bf16 v[102:105], v[150:153], v[224:227], v[102:105]
	v_mfma_f32_16x16x32_bf16 v[98:101], v[158:161], v[224:227], v[98:101]
	v_mfma_f32_16x16x32_bf16 v[122:125], v[154:157], v[204:207], v[122:125]
	v_mfma_f32_16x16x32_bf16 v[126:129], v[162:165], v[204:207], v[126:129]
	v_mfma_f32_16x16x32_bf16 v[118:121], v[154:157], v[212:215], v[118:121]
	v_mfma_f32_16x16x32_bf16 v[114:117], v[162:165], v[212:215], v[114:117]
	v_mfma_f32_16x16x32_bf16 v[110:113], v[154:157], v[220:223], v[110:113]
	v_mfma_f32_16x16x32_bf16 v[106:109], v[162:165], v[220:223], v[106:109]
	v_mfma_f32_16x16x32_bf16 v[102:105], v[154:157], v[228:231], v[102:105]
	v_mfma_f32_16x16x32_bf16 v[98:101], v[162:165], v[228:231], v[98:101]
	s_setprio 0
	s_setprio 1
	v_mfma_f32_16x16x32_bf16 v[62:65], v[180:183], v[200:203], v[62:65]
	v_mfma_f32_16x16x32_bf16 v[58:61], v[188:191], v[200:203], v[58:61]
	v_mfma_f32_16x16x32_bf16 v[54:57], v[180:183], v[208:211], v[54:57]
	v_mfma_f32_16x16x32_bf16 v[50:53], v[188:191], v[208:211], v[50:53]
	v_mfma_f32_16x16x32_bf16 v[46:49], v[180:183], v[216:219], v[46:49]
	v_mfma_f32_16x16x32_bf16 v[42:45], v[188:191], v[216:219], v[42:45]
	v_mfma_f32_16x16x32_bf16 v[38:41], v[180:183], v[224:227], v[38:41]
	v_mfma_f32_16x16x32_bf16 v[34:37], v[188:191], v[224:227], v[34:37]
	v_mfma_f32_16x16x32_bf16 v[62:65], v[184:187], v[204:207], v[62:65]
	v_mfma_f32_16x16x32_bf16 v[58:61], v[192:195], v[204:207], v[58:61]
	v_mfma_f32_16x16x32_bf16 v[54:57], v[184:187], v[212:215], v[54:57]
	v_mfma_f32_16x16x32_bf16 v[50:53], v[192:195], v[212:215], v[50:53]
	v_mfma_f32_16x16x32_bf16 v[46:49], v[184:187], v[220:223], v[46:49]
	v_mfma_f32_16x16x32_bf16 v[42:45], v[192:195], v[220:223], v[42:45]
	v_mfma_f32_16x16x32_bf16 v[38:41], v[184:187], v[228:231], v[38:41]
	v_mfma_f32_16x16x32_bf16 v[34:37], v[192:195], v[228:231], v[34:37]
	s_setprio 0
	s_barrier
	s_add_i32 s10, s54, s16
	v_lshl_add_u64 v[196:197], v[196:197], 0, s[22:23]
	s_mov_b32 m0, s10
	ds_read_b128 v[200:203], v174 offset:49152
	ds_read_b128 v[204:207], v174 offset:50176
	ds_read_b128 v[208:211], v174 offset:51200
	ds_read_b128 v[212:215], v174 offset:52224
	ds_read_b128 v[216:219], v174 offset:53248
	ds_read_b128 v[220:223], v174 offset:54272
	ds_read_b128 v[224:227], v174 offset:55296
	ds_read_b128 v[228:231], v174 offset:56320
	global_load_lds_dwordx4 v[196:197], off
	v_lshl_add_u64 v[196:197], v[232:233], 0, s[22:23]
	s_add_i32 m0, s10, 0x2000
	s_add_i32 s10, s55, s16
	global_load_lds_dwordx4 v[196:197], off
	v_lshl_add_u64 v[196:197], v[234:235], 0, s[22:23]
	s_mov_b32 m0, s10
	s_nop 0
	global_load_lds_dwordx4 v[196:197], off
	v_lshl_add_u64 v[196:197], v[236:237], 0, s[22:23]
	s_add_i32 m0, s10, 0x2000
	s_nop 0
	global_load_lds_dwordx4 v[196:197], off
	v_lshl_add_u64 v[196:197], v[238:239], 0, s[22:23]
	s_mov_b32 m0, s57
	s_nop 0
	global_load_lds_dwordx4 v[196:197], off
	v_lshl_add_u64 v[196:197], v[240:241], 0, s[22:23]
	s_mov_b32 m0, s58
	s_nop 0
	global_load_lds_dwordx4 v[196:197], off
	s_waitcnt vmcnt(8)
	s_waitcnt lgkmcnt(0)
	s_barrier
	s_setprio 1
	s_waitcnt lgkmcnt(0)
	v_mfma_f32_16x16x32_bf16 v[94:97], v[150:153], v[200:203], v[94:97]
	v_mfma_f32_16x16x32_bf16 v[90:93], v[158:161], v[200:203], v[90:93]
	v_mfma_f32_16x16x32_bf16 v[86:89], v[150:153], v[208:211], v[86:89]
	v_mfma_f32_16x16x32_bf16 v[82:85], v[158:161], v[208:211], v[82:85]
	v_mfma_f32_16x16x32_bf16 v[78:81], v[150:153], v[216:219], v[78:81]
	v_mfma_f32_16x16x32_bf16 v[74:77], v[158:161], v[216:219], v[74:77]
	v_mfma_f32_16x16x32_bf16 v[70:73], v[150:153], v[224:227], v[70:73]
	v_mfma_f32_16x16x32_bf16 v[66:69], v[158:161], v[224:227], v[66:69]
	v_mfma_f32_16x16x32_bf16 v[94:97], v[154:157], v[204:207], v[94:97]
	v_mfma_f32_16x16x32_bf16 v[90:93], v[162:165], v[204:207], v[90:93]
	v_mfma_f32_16x16x32_bf16 v[86:89], v[154:157], v[212:215], v[86:89]
	v_mfma_f32_16x16x32_bf16 v[82:85], v[162:165], v[212:215], v[82:85]
	v_mfma_f32_16x16x32_bf16 v[78:81], v[154:157], v[220:223], v[78:81]
	v_mfma_f32_16x16x32_bf16 v[74:77], v[162:165], v[220:223], v[74:77]
	v_mfma_f32_16x16x32_bf16 v[70:73], v[154:157], v[228:231], v[70:73]
	v_mfma_f32_16x16x32_bf16 v[66:69], v[162:165], v[228:231], v[66:69]
	s_setprio 0
	s_setprio 1
	v_mfma_f32_16x16x32_bf16 v[30:33], v[180:183], v[200:203], v[30:33]
	v_mfma_f32_16x16x32_bf16 v[26:29], v[188:191], v[200:203], v[26:29]
	v_mfma_f32_16x16x32_bf16 v[22:25], v[180:183], v[208:211], v[22:25]
	v_mfma_f32_16x16x32_bf16 v[18:21], v[188:191], v[208:211], v[18:21]
	v_mfma_f32_16x16x32_bf16 v[14:17], v[180:183], v[216:219], v[14:17]
	v_mfma_f32_16x16x32_bf16 v[10:13], v[188:191], v[216:219], v[10:13]
	v_mfma_f32_16x16x32_bf16 v[6:9], v[180:183], v[224:227], v[6:9]
	v_mfma_f32_16x16x32_bf16 v[2:5], v[188:191], v[224:227], v[2:5]
	v_mfma_f32_16x16x32_bf16 v[30:33], v[184:187], v[204:207], v[30:33]
	v_mfma_f32_16x16x32_bf16 v[26:29], v[192:195], v[204:207], v[26:29]
	v_mfma_f32_16x16x32_bf16 v[22:25], v[184:187], v[212:215], v[22:25]
	v_mfma_f32_16x16x32_bf16 v[18:21], v[192:195], v[212:215], v[18:21]
	v_mfma_f32_16x16x32_bf16 v[14:17], v[184:187], v[220:223], v[14:17]
	v_mfma_f32_16x16x32_bf16 v[10:13], v[192:195], v[220:223], v[10:13]
	v_mfma_f32_16x16x32_bf16 v[6:9], v[184:187], v[228:231], v[6:9]
	v_mfma_f32_16x16x32_bf16 v[2:5], v[192:195], v[228:231], v[2:5]
	s_setprio 0
	s_barrier
	s_add_u32 s8, s8, 0x100
	s_addc_u32 s9, s9, 0
	s_add_u32 s51, s51, 0x100
	s_addc_u32 s52, s52, 0
	s_cmp_ge_i32 s53, s61
	s_mov_b32 s10, s53
	s_cbranch_scc0 .LBB0_1337
	s_getpc_b64 s[98:99]
	s_mov_b32 m0, 0x22800
	v_lshlrev_b32_e32 v228, 7, v0
	global_load_lds_dword v228, s[98:99]

.LBB0_1556:
	ds_read_b128 v[150:153], v172
	ds_read_b128 v[154:157], v172 offset:1024
	ds_read_b128 v[158:161], v172 offset:2048
	ds_read_b128 v[162:165], v172 offset:3072
	ds_read_b128 v[180:183], v173
	ds_read_b128 v[184:187], v173 offset:1024
	ds_read_b128 v[188:191], v173 offset:2048
	ds_read_b128 v[192:195], v173 offset:3072
	s_add_i32 s48, s8, 2
	s_add_u32 s49, s6, 0x80
	s_addc_u32 s9, s7, 0
	s_cmp_eq_u32 s64, s8
	s_cselect_b32 s8, s31, s49
	s_cselect_b32 s9, s3, s9
	s_cselect_b32 s85, s35, s47
	s_cselect_b32 s84, s45, s46
	v_lshl_add_u64 v[196:197], s[6:7], 0, v[146:147]
	s_add_i32 m0, s29, 0xc000
	ds_read_b128 v[200:203], v174
	ds_read_b128 v[204:207], v174 offset:1024
	ds_read_b128 v[208:211], v174 offset:2048
	ds_read_b128 v[212:215], v174 offset:3072
	ds_read_b128 v[216:219], v174 offset:4096
	ds_read_b128 v[220:223], v174 offset:5120
	ds_read_b128 v[224:227], v174 offset:6144
	ds_read_b128 v[228:231], v174 offset:7168
	global_load_lds_dwordx4 v[196:197], off
	v_lshl_add_u64 v[196:197], s[6:7], 0, v[148:149]
	s_add_i32 m0, s29, 0xe000
	s_nop 0
	global_load_lds_dwordx4 v[196:197], off
	s_waitcnt vmcnt(8)
	s_waitcnt lgkmcnt(0)
	s_barrier
	s_setprio 1
	s_waitcnt lgkmcnt(0)
	v_mfma_f32_16x16x32_bf16 v[122:125], v[150:153], v[200:203], v[122:125]
	v_mfma_f32_16x16x32_bf16 v[126:129], v[158:161], v[200:203], v[126:129]
	v_mfma_f32_16x16x32_bf16 v[118:121], v[150:153], v[208:211], v[118:121]
	v_mfma_f32_16x16x32_bf16 v[114:117], v[158:161], v[208:211], v[114:117]
	v_mfma_f32_16x16x32_bf16 v[110:113], v[150:153], v[216:219], v[110:113]
	v_mfma_f32_16x16x32_bf16 v[106:109], v[158:161], v[216:219], v[106:109]
	v_mfma_f32_16x16x32_bf16 v[102:105], v[150:153], v[224:227], v[102:105]
	v_mfma_f32_16x16x32_bf16 v[98:101], v[158:161], v[224:227], v[98:101]
	v_mfma_f32_16x16x32_bf16 v[122:125], v[154:157], v[204:207], v[122:125]
	v_mfma_f32_16x16x32_bf16 v[126:129], v[162:165], v[204:207], v[126:129]
	v_mfma_f32_16x16x32_bf16 v[118:121], v[154:157], v[212:215], v[118:121]
	v_mfma_f32_16x16x32_bf16 v[114:117], v[162:165], v[212:215], v[114:117]
	v_mfma_f32_16x16x32_bf16 v[110:113], v[154:157], v[220:223], v[110:113]
	v_mfma_f32_16x16x32_bf16 v[106:109], v[162:165], v[220:223], v[106:109]
	v_mfma_f32_16x16x32_bf16 v[102:105], v[154:157], v[228:231], v[102:105]
	v_mfma_f32_16x16x32_bf16 v[98:101], v[162:165], v[228:231], v[98:101]
	s_setprio 0
	s_setprio 1
	v_mfma_f32_16x16x32_bf16 v[62:65], v[180:183], v[200:203], v[62:65]
	v_mfma_f32_16x16x32_bf16 v[58:61], v[188:191], v[200:203], v[58:61]
	v_mfma_f32_16x16x32_bf16 v[54:57], v[180:183], v[208:211], v[54:57]
	v_mfma_f32_16x16x32_bf16 v[50:53], v[188:191], v[208:211], v[50:53]
	v_mfma_f32_16x16x32_bf16 v[46:49], v[180:183], v[216:219], v[46:49]
	v_mfma_f32_16x16x32_bf16 v[42:45], v[188:191], v[216:219], v[42:45]
	v_mfma_f32_16x16x32_bf16 v[38:41], v[180:183], v[224:227], v[38:41]
	v_mfma_f32_16x16x32_bf16 v[34:37], v[188:191], v[224:227], v[34:37]
	v_mfma_f32_16x16x32_bf16 v[62:65], v[184:187], v[204:207], v[62:65]
	v_mfma_f32_16x16x32_bf16 v[58:61], v[192:195], v[204:207], v[58:61]
	v_mfma_f32_16x16x32_bf16 v[54:57], v[184:187], v[212:215], v[54:57]
	v_mfma_f32_16x16x32_bf16 v[50:53], v[192:195], v[212:215], v[50:53]
	v_mfma_f32_16x16x32_bf16 v[46:49], v[184:187], v[220:223], v[46:49]
	v_mfma_f32_16x16x32_bf16 v[42:45], v[192:195], v[220:223], v[42:45]
	v_mfma_f32_16x16x32_bf16 v[38:41], v[184:187], v[228:231], v[38:41]
	v_mfma_f32_16x16x32_bf16 v[34:37], v[192:195], v[228:231], v[34:37]
	s_setprio 0
	s_barrier
	s_add_i32 s49, s68, s51
	v_lshl_add_u64 v[196:197], s[84:85], 0, v[132:133]
	s_mov_b32 m0, s49
	ds_read_b128 v[200:203], v174 offset:16384
	ds_read_b128 v[204:207], v174 offset:17408
	ds_read_b128 v[208:211], v174 offset:18432
	ds_read_b128 v[212:215], v174 offset:19456
	ds_read_b128 v[216:219], v174 offset:20480
	ds_read_b128 v[220:223], v174 offset:21504
	ds_read_b128 v[224:227], v174 offset:22528
	ds_read_b128 v[228:231], v174 offset:23552
	global_load_lds_dwordx4 v[196:197], off
	s_add_i32 m0, s49, 0x2000
	v_lshl_add_u64 v[232:233], s[84:85], 0, v[136:137]
	s_add_u32 s84, s84, s10
	s_addc_u32 s85, s85, s11
	s_add_i32 s49, s69, s51
	global_load_lds_dwordx4 v[232:233], off
	v_lshl_add_u64 v[234:235], s[84:85], 0, v[132:133]
	s_mov_b32 m0, s49
	v_lshl_add_u64 v[236:237], s[84:85], 0, v[136:137]
	global_load_lds_dwordx4 v[234:235], off
	s_add_i32 m0, s49, 0x2000
	v_lshl_add_u64 v[238:239], s[8:9], 0, v[130:131]
	global_load_lds_dwordx4 v[236:237], off
	s_mov_b32 m0, s29
	v_lshl_add_u64 v[240:241], s[8:9], 0, v[134:135]
	global_load_lds_dwordx4 v[238:239], off
	s_mov_b32 m0, s43
	s_nop 0
	global_load_lds_dwordx4 v[240:241], off
	s_waitcnt vmcnt(8)
	s_waitcnt lgkmcnt(0)
	s_barrier
	s_setprio 1
	s_waitcnt lgkmcnt(0)
	v_mfma_f32_16x16x32_bf16 v[94:97], v[150:153], v[200:203], v[94:97]
	v_mfma_f32_16x16x32_bf16 v[90:93], v[158:161], v[200:203], v[90:93]
	v_mfma_f32_16x16x32_bf16 v[86:89], v[150:153], v[208:211], v[86:89]
	v_mfma_f32_16x16x32_bf16 v[82:85], v[158:161], v[208:211], v[82:85]
	v_mfma_f32_16x16x32_bf16 v[78:81], v[150:153], v[216:219], v[78:81]
	v_mfma_f32_16x16x32_bf16 v[74:77], v[158:161], v[216:219], v[74:77]
	v_mfma_f32_16x16x32_bf16 v[70:73], v[150:153], v[224:227], v[70:73]
	v_mfma_f32_16x16x32_bf16 v[66:69], v[158:161], v[224:227], v[66:69]
	v_mfma_f32_16x16x32_bf16 v[94:97], v[154:157], v[204:207], v[94:97]
	v_mfma_f32_16x16x32_bf16 v[90:93], v[162:165], v[204:207], v[90:93]
	v_mfma_f32_16x16x32_bf16 v[86:89], v[154:157], v[212:215], v[86:89]
	v_mfma_f32_16x16x32_bf16 v[82:85], v[162:165], v[212:215], v[82:85]
	v_mfma_f32_16x16x32_bf16 v[78:81], v[154:157], v[220:223], v[78:81]
	v_mfma_f32_16x16x32_bf16 v[74:77], v[162:165], v[220:223], v[74:77]
	v_mfma_f32_16x16x32_bf16 v[70:73], v[154:157], v[228:231], v[70:73]
	v_mfma_f32_16x16x32_bf16 v[66:69], v[162:165], v[228:231], v[66:69]
	s_setprio 0
	s_setprio 1
	v_mfma_f32_16x16x32_bf16 v[30:33], v[180:183], v[200:203], v[30:33]
	v_mfma_f32_16x16x32_bf16 v[26:29], v[188:191], v[200:203], v[26:29]
	v_mfma_f32_16x16x32_bf16 v[22:25], v[180:183], v[208:211], v[22:25]
	v_mfma_f32_16x16x32_bf16 v[18:21], v[188:191], v[208:211], v[18:21]
	v_mfma_f32_16x16x32_bf16 v[14:17], v[180:183], v[216:219], v[14:17]
	v_mfma_f32_16x16x32_bf16 v[10:13], v[188:191], v[216:219], v[10:13]
	v_mfma_f32_16x16x32_bf16 v[6:9], v[180:183], v[224:227], v[6:9]
	v_mfma_f32_16x16x32_bf16 v[2:5], v[188:191], v[224:227], v[2:5]
	v_mfma_f32_16x16x32_bf16 v[30:33], v[184:187], v[204:207], v[30:33]
	v_mfma_f32_16x16x32_bf16 v[26:29], v[192:195], v[204:207], v[26:29]
	v_mfma_f32_16x16x32_bf16 v[22:25], v[184:187], v[212:215], v[22:25]
	v_mfma_f32_16x16x32_bf16 v[18:21], v[192:195], v[212:215], v[18:21]
	v_mfma_f32_16x16x32_bf16 v[14:17], v[184:187], v[220:223], v[14:17]
	v_mfma_f32_16x16x32_bf16 v[10:13], v[192:195], v[220:223], v[10:13]
	v_mfma_f32_16x16x32_bf16 v[6:9], v[184:187], v[228:231], v[6:9]
	v_mfma_f32_16x16x32_bf16 v[2:5], v[192:195], v[228:231], v[2:5]
	s_setprio 0
	s_barrier
	s_add_i32 s49, 0, 0x18000
	v_add_u32_e32 v138, s49, v166
	s_add_i32 s84, 0, 0x1c000
	ds_read_b128 v[150:153], v138
	ds_read_b128 v[154:157], v138 offset:1024
	ds_read_b128 v[158:161], v138 offset:2048
	ds_read_b128 v[162:165], v138 offset:3072
	v_add_u32_e32 v138, s84, v166
	ds_read_b128 v[180:183], v138
	ds_read_b128 v[184:187], v138 offset:1024
	ds_read_b128 v[188:191], v138 offset:2048
	ds_read_b128 v[192:195], v138 offset:3072
	s_add_u32 s8, s8, s10
	s_addc_u32 s9, s9, s11
	s_mov_b32 m0, s53
	v_lshl_add_u64 v[242:243], s[8:9], 0, v[130:131]
	ds_read_b128 v[200:203], v174 offset:32768
	ds_read_b128 v[204:207], v174 offset:33792
	ds_read_b128 v[208:211], v174 offset:34816
	ds_read_b128 v[212:215], v174 offset:35840
	ds_read_b128 v[216:219], v174 offset:36864
	ds_read_b128 v[220:223], v174 offset:37888
	ds_read_b128 v[224:227], v174 offset:38912
	ds_read_b128 v[228:231], v174 offset:39936
	global_load_lds_dwordx4 v[242:243], off
	v_lshl_add_u64 v[242:243], s[8:9], 0, v[134:135]
	s_mov_b32 m0, s54
	s_nop 0
	global_load_lds_dwordx4 v[242:243], off
	s_waitcnt vmcnt(8)
	s_waitcnt lgkmcnt(0)
	s_barrier
	s_setprio 1
	s_waitcnt lgkmcnt(0)
	v_mfma_f32_16x16x32_bf16 v[122:125], v[150:153], v[200:203], v[122:125]
	v_mfma_f32_16x16x32_bf16 v[126:129], v[158:161], v[200:203], v[126:129]
	v_mfma_f32_16x16x32_bf16 v[118:121], v[150:153], v[208:211], v[118:121]
	v_mfma_f32_16x16x32_bf16 v[114:117], v[158:161], v[208:211], v[114:117]
	v_mfma_f32_16x16x32_bf16 v[110:113], v[150:153], v[216:219], v[110:113]
	v_mfma_f32_16x16x32_bf16 v[106:109], v[158:161], v[216:219], v[106:109]
	v_mfma_f32_16x16x32_bf16 v[102:105], v[150:153], v[224:227], v[102:105]
	v_mfma_f32_16x16x32_bf16 v[98:101], v[158:161], v[224:227], v[98:101]
	v_mfma_f32_16x16x32_bf16 v[122:125], v[154:157], v[204:207], v[122:125]
	v_mfma_f32_16x16x32_bf16 v[126:129], v[162:165], v[204:207], v[126:129]
	v_mfma_f32_16x16x32_bf16 v[118:121], v[154:157], v[212:215], v[118:121]
	v_mfma_f32_16x16x32_bf16 v[114:117], v[162:165], v[212:215], v[114:117]
	v_mfma_f32_16x16x32_bf16 v[110:113], v[154:157], v[220:223], v[110:113]
	v_mfma_f32_16x16x32_bf16 v[106:109], v[162:165], v[220:223], v[106:109]
	v_mfma_f32_16x16x32_bf16 v[102:105], v[154:157], v[228:231], v[102:105]
	v_mfma_f32_16x16x32_bf16 v[98:101], v[162:165], v[228:231], v[98:101]
	s_setprio 0
	s_setprio 1
	v_mfma_f32_16x16x32_bf16 v[62:65], v[180:183], v[200:203], v[62:65]
	v_mfma_f32_16x16x32_bf16 v[58:61], v[188:191], v[200:203], v[58:61]
	v_mfma_f32_16x16x32_bf16 v[54:57], v[180:183], v[208:211], v[54:57]
	v_mfma_f32_16x16x32_bf16 v[50:53], v[188:191], v[208:211], v[50:53]
	v_mfma_f32_16x16x32_bf16 v[46:49], v[180:183], v[216:219], v[46:49]
	v_mfma_f32_16x16x32_bf16 v[42:45], v[188:191], v[216:219], v[42:45]
	v_mfma_f32_16x16x32_bf16 v[38:41], v[180:183], v[224:227], v[38:41]
	v_mfma_f32_16x16x32_bf16 v[34:37], v[188:191], v[224:227], v[34:37]
	v_mfma_f32_16x16x32_bf16 v[62:65], v[184:187], v[204:207], v[62:65]
	v_mfma_f32_16x16x32_bf16 v[58:61], v[192:195], v[204:207], v[58:61]
	v_mfma_f32_16x16x32_bf16 v[54:57], v[184:187], v[212:215], v[54:57]
	v_mfma_f32_16x16x32_bf16 v[50:53], v[192:195], v[212:215], v[50:53]
	v_mfma_f32_16x16x32_bf16 v[46:49], v[184:187], v[220:223], v[46:49]
	v_mfma_f32_16x16x32_bf16 v[42:45], v[192:195], v[220:223], v[42:45]
	v_mfma_f32_16x16x32_bf16 v[38:41], v[184:187], v[228:231], v[38:41]
	v_mfma_f32_16x16x32_bf16 v[34:37], v[192:195], v[228:231], v[34:37]
	s_setprio 0
	s_barrier
	s_add_i32 s8, s49, s51
	v_lshl_add_u64 v[196:197], v[196:197], 0, s[14:15]
	s_mov_b32 m0, s8
	ds_read_b128 v[200:203], v174 offset:49152
	ds_read_b128 v[204:207], v174 offset:50176
	ds_read_b128 v[208:211], v174 offset:51200
	ds_read_b128 v[212:215], v174 offset:52224
	ds_read_b128 v[216:219], v174 offset:53248
	ds_read_b128 v[220:223], v174 offset:54272
	ds_read_b128 v[224:227], v174 offset:55296
	ds_read_b128 v[228:231], v174 offset:56320
	global_load_lds_dwordx4 v[196:197], off
	v_lshl_add_u64 v[196:197], v[232:233], 0, s[14:15]
	s_add_i32 m0, s8, 0x2000
	s_add_i32 s8, s84, s51
	global_load_lds_dwordx4 v[196:197], off
	v_lshl_add_u64 v[196:197], v[234:235], 0, s[14:15]
	s_mov_b32 m0, s8
	s_nop 0
	global_load_lds_dwordx4 v[196:197], off
	v_lshl_add_u64 v[196:197], v[236:237], 0, s[14:15]
	s_add_i32 m0, s8, 0x2000
	s_nop 0
	global_load_lds_dwordx4 v[196:197], off
	v_lshl_add_u64 v[196:197], v[238:239], 0, s[14:15]
	s_mov_b32 m0, s58
	s_nop 0
	global_load_lds_dwordx4 v[196:197], off
	v_lshl_add_u64 v[196:197], v[240:241], 0, s[14:15]
	s_mov_b32 m0, s59
	s_nop 0
	global_load_lds_dwordx4 v[196:197], off
	s_waitcnt vmcnt(8)
	s_waitcnt lgkmcnt(0)
	s_barrier
	s_setprio 1
	s_waitcnt lgkmcnt(0)
	v_mfma_f32_16x16x32_bf16 v[94:97], v[150:153], v[200:203], v[94:97]
	v_mfma_f32_16x16x32_bf16 v[90:93], v[158:161], v[200:203], v[90:93]
	v_mfma_f32_16x16x32_bf16 v[86:89], v[150:153], v[208:211], v[86:89]
	v_mfma_f32_16x16x32_bf16 v[82:85], v[158:161], v[208:211], v[82:85]
	v_mfma_f32_16x16x32_bf16 v[78:81], v[150:153], v[216:219], v[78:81]
	v_mfma_f32_16x16x32_bf16 v[74:77], v[158:161], v[216:219], v[74:77]
	v_mfma_f32_16x16x32_bf16 v[70:73], v[150:153], v[224:227], v[70:73]
	v_mfma_f32_16x16x32_bf16 v[66:69], v[158:161], v[224:227], v[66:69]
	v_mfma_f32_16x16x32_bf16 v[94:97], v[154:157], v[204:207], v[94:97]
	v_mfma_f32_16x16x32_bf16 v[90:93], v[162:165], v[204:207], v[90:93]
	v_mfma_f32_16x16x32_bf16 v[86:89], v[154:157], v[212:215], v[86:89]
	v_mfma_f32_16x16x32_bf16 v[82:85], v[162:165], v[212:215], v[82:85]
	v_mfma_f32_16x16x32_bf16 v[78:81], v[154:157], v[220:223], v[78:81]
	v_mfma_f32_16x16x32_bf16 v[74:77], v[162:165], v[220:223], v[74:77]
	v_mfma_f32_16x16x32_bf16 v[70:73], v[154:157], v[228:231], v[70:73]
	v_mfma_f32_16x16x32_bf16 v[66:69], v[162:165], v[228:231], v[66:69]
	s_setprio 0
	s_setprio 1
	v_mfma_f32_16x16x32_bf16 v[30:33], v[180:183], v[200:203], v[30:33]
	v_mfma_f32_16x16x32_bf16 v[26:29], v[188:191], v[200:203], v[26:29]
	v_mfma_f32_16x16x32_bf16 v[22:25], v[180:183], v[208:211], v[22:25]
	v_mfma_f32_16x16x32_bf16 v[18:21], v[188:191], v[208:211], v[18:21]
	v_mfma_f32_16x16x32_bf16 v[14:17], v[180:183], v[216:219], v[14:17]
	v_mfma_f32_16x16x32_bf16 v[10:13], v[188:191], v[216:219], v[10:13]
	v_mfma_f32_16x16x32_bf16 v[6:9], v[180:183], v[224:227], v[6:9]
	v_mfma_f32_16x16x32_bf16 v[2:5], v[188:191], v[224:227], v[2:5]
	v_mfma_f32_16x16x32_bf16 v[30:33], v[184:187], v[204:207], v[30:33]
	v_mfma_f32_16x16x32_bf16 v[26:29], v[192:195], v[204:207], v[26:29]
	v_mfma_f32_16x16x32_bf16 v[22:25], v[184:187], v[212:215], v[22:25]
	v_mfma_f32_16x16x32_bf16 v[18:21], v[192:195], v[212:215], v[18:21]
	v_mfma_f32_16x16x32_bf16 v[14:17], v[184:187], v[220:223], v[14:17]
	v_mfma_f32_16x16x32_bf16 v[10:13], v[192:195], v[220:223], v[10:13]
	v_mfma_f32_16x16x32_bf16 v[6:9], v[184:187], v[228:231], v[6:9]
	v_mfma_f32_16x16x32_bf16 v[2:5], v[192:195], v[228:231], v[2:5]
	s_setprio 0
	s_barrier
	s_add_u32 s6, s6, 0x100
	s_addc_u32 s7, s7, 0
	s_add_u32 s46, s46, 0x100
	s_addc_u32 s47, s47, 0
	s_cmp_ge_i32 s48, s61
	s_mov_b32 s8, s48
	s_cbranch_scc0 .LBB0_1556
	s_getpc_b64 s[98:99]
	s_mov_b32 m0, 0x22800
	v_lshlrev_b32_e32 v228, 7, v0
	global_load_lds_dword v228, s[98:99]

.LBB0_1987:
	v_add_u32_e32 v2, s58, v199
	ds_read_b128 v[134:137], v2
	ds_read_b128 v[138:141], v2 offset:1024
	ds_read_b128 v[142:145], v2 offset:2048
	ds_read_b128 v[146:149], v2 offset:3072
	v_add_u32_e32 v2, s59, v199
	ds_read_b128 v[150:153], v2
	ds_read_b128 v[154:157], v2 offset:1024
	ds_read_b128 v[158:161], v2 offset:2048
	ds_read_b128 v[162:165], v2 offset:3072
	s_add_i32 s63, s40, 2
	s_add_u32 s64, s38, 0x80
	s_addc_u32 s41, s39, 0
	s_cmp_eq_u32 s57, s40
	s_cselect_b32 s40, s3, s64
	s_cselect_b32 s41, s1, s41
	s_cselect_b32 s65, s10, s62
	s_cselect_b32 s64, s27, s29
	v_lshl_add_u64 v[4:5], s[38:39], 0, v[212:213]
	s_add_i32 m0, s45, 0xc000
	ds_read_b128 v[166:169], v228
	ds_read_b128 v[170:173], v228 offset:1024
	ds_read_b128 v[174:177], v228 offset:2048
	ds_read_b128 v[178:181], v228 offset:3072
	ds_read_b128 v[182:185], v228 offset:4096
	ds_read_b128 v[186:189], v228 offset:5120
	ds_read_b128 v[190:193], v228 offset:6144
	ds_read_b128 v[194:197], v228 offset:7168
	global_load_lds_dwordx4 v[4:5], off
	v_lshl_add_u64 v[4:5], s[38:39], 0, v[214:215]
	s_add_i32 m0, s45, 0xe000
	s_nop 0
	global_load_lds_dwordx4 v[4:5], off
	s_waitcnt vmcnt(8)
	s_waitcnt lgkmcnt(0)
	s_barrier
	s_setprio 1
	s_waitcnt lgkmcnt(0)
	v_mfma_f32_16x16x32_bf16 v[130:133], v[134:137], v[166:169], v[130:133]
	v_mfma_f32_16x16x32_bf16 v[126:129], v[142:145], v[166:169], v[126:129]
	v_mfma_f32_16x16x32_bf16 v[122:125], v[134:137], v[174:177], v[122:125]
	v_mfma_f32_16x16x32_bf16 v[118:121], v[142:145], v[174:177], v[118:121]
	v_mfma_f32_16x16x32_bf16 v[114:117], v[134:137], v[182:185], v[114:117]
	v_mfma_f32_16x16x32_bf16 v[110:113], v[142:145], v[182:185], v[110:113]
	v_mfma_f32_16x16x32_bf16 v[106:109], v[134:137], v[190:193], v[106:109]
	v_mfma_f32_16x16x32_bf16 v[102:105], v[142:145], v[190:193], v[102:105]
	v_mfma_f32_16x16x32_bf16 v[130:133], v[138:141], v[170:173], v[130:133]
	v_mfma_f32_16x16x32_bf16 v[126:129], v[146:149], v[170:173], v[126:129]
	v_mfma_f32_16x16x32_bf16 v[122:125], v[138:141], v[178:181], v[122:125]
	v_mfma_f32_16x16x32_bf16 v[118:121], v[146:149], v[178:181], v[118:121]
	v_mfma_f32_16x16x32_bf16 v[114:117], v[138:141], v[186:189], v[114:117]
	v_mfma_f32_16x16x32_bf16 v[110:113], v[146:149], v[186:189], v[110:113]
	v_mfma_f32_16x16x32_bf16 v[106:109], v[138:141], v[194:197], v[106:109]
	v_mfma_f32_16x16x32_bf16 v[102:105], v[146:149], v[194:197], v[102:105]
	s_setprio 0
	s_setprio 1
	v_mfma_f32_16x16x32_bf16 v[98:101], v[150:153], v[166:169], v[98:101]
	v_mfma_f32_16x16x32_bf16 v[94:97], v[158:161], v[166:169], v[94:97]
	v_mfma_f32_16x16x32_bf16 v[90:93], v[150:153], v[174:177], v[90:93]
	v_mfma_f32_16x16x32_bf16 v[86:89], v[158:161], v[174:177], v[86:89]
	v_mfma_f32_16x16x32_bf16 v[82:85], v[150:153], v[182:185], v[82:85]
	v_mfma_f32_16x16x32_bf16 v[78:81], v[158:161], v[182:185], v[78:81]
	v_mfma_f32_16x16x32_bf16 v[74:77], v[150:153], v[190:193], v[74:77]
	v_mfma_f32_16x16x32_bf16 v[70:73], v[158:161], v[190:193], v[70:73]
	v_mfma_f32_16x16x32_bf16 v[98:101], v[154:157], v[170:173], v[98:101]
	v_mfma_f32_16x16x32_bf16 v[94:97], v[162:165], v[170:173], v[94:97]
	v_mfma_f32_16x16x32_bf16 v[90:93], v[154:157], v[178:181], v[90:93]
	v_mfma_f32_16x16x32_bf16 v[86:89], v[162:165], v[178:181], v[86:89]
	v_mfma_f32_16x16x32_bf16 v[82:85], v[154:157], v[186:189], v[82:85]
	v_mfma_f32_16x16x32_bf16 v[78:81], v[162:165], v[186:189], v[78:81]
	v_mfma_f32_16x16x32_bf16 v[74:77], v[154:157], v[194:197], v[74:77]
	v_mfma_f32_16x16x32_bf16 v[70:73], v[162:165], v[194:197], v[70:73]
	s_setprio 0
	s_barrier
	s_add_i32 s66, s58, s2
	v_lshl_add_u64 v[216:217], s[64:65], 0, v[202:203]
	s_mov_b32 m0, s66
	ds_read_b128 v[166:169], v228 offset:16384
	ds_read_b128 v[170:173], v228 offset:17408
	ds_read_b128 v[174:177], v228 offset:18432
	ds_read_b128 v[178:181], v228 offset:19456
	ds_read_b128 v[182:185], v228 offset:20480
	ds_read_b128 v[186:189], v228 offset:21504
	ds_read_b128 v[190:193], v228 offset:22528
	ds_read_b128 v[194:197], v228 offset:23552
	global_load_lds_dwordx4 v[216:217], off
	s_add_i32 m0, s66, 0x2000
	v_lshl_add_u64 v[218:219], s[64:65], 0, v[206:207]
	s_add_u32 s64, s64, s8
	s_addc_u32 s65, s65, s9
	s_add_i32 s66, s59, s2
	global_load_lds_dwordx4 v[218:219], off
	v_lshl_add_u64 v[220:221], s[64:65], 0, v[202:203]
	s_mov_b32 m0, s66
	v_lshl_add_u64 v[222:223], s[64:65], 0, v[206:207]
	global_load_lds_dwordx4 v[220:221], off
	s_add_i32 m0, s66, 0x2000
	v_lshl_add_u64 v[230:231], s[40:41], 0, v[200:201]
	global_load_lds_dwordx4 v[222:223], off
	s_mov_b32 m0, s45
	v_lshl_add_u64 v[232:233], s[40:41], 0, v[204:205]
	global_load_lds_dwordx4 v[230:231], off
	s_mov_b32 m0, s46
	s_nop 0
	global_load_lds_dwordx4 v[232:233], off
	s_waitcnt vmcnt(8)
	s_waitcnt lgkmcnt(0)
	s_barrier
	s_setprio 1
	s_waitcnt lgkmcnt(0)
	v_mfma_f32_16x16x32_bf16 v[66:69], v[134:137], v[166:169], v[66:69]
	v_mfma_f32_16x16x32_bf16 v[62:65], v[142:145], v[166:169], v[62:65]
	v_mfma_f32_16x16x32_bf16 v[58:61], v[134:137], v[174:177], v[58:61]
	v_mfma_f32_16x16x32_bf16 v[54:57], v[142:145], v[174:177], v[54:57]
	v_mfma_f32_16x16x32_bf16 v[50:53], v[134:137], v[182:185], v[50:53]
	v_mfma_f32_16x16x32_bf16 v[46:49], v[142:145], v[182:185], v[46:49]
	v_mfma_f32_16x16x32_bf16 v[42:45], v[134:137], v[190:193], v[42:45]
	v_mfma_f32_16x16x32_bf16 v[38:41], v[142:145], v[190:193], v[38:41]
	v_mfma_f32_16x16x32_bf16 v[66:69], v[138:141], v[170:173], v[66:69]
	v_mfma_f32_16x16x32_bf16 v[62:65], v[146:149], v[170:173], v[62:65]
	v_mfma_f32_16x16x32_bf16 v[58:61], v[138:141], v[178:181], v[58:61]
	v_mfma_f32_16x16x32_bf16 v[54:57], v[146:149], v[178:181], v[54:57]
	v_mfma_f32_16x16x32_bf16 v[50:53], v[138:141], v[186:189], v[50:53]
	v_mfma_f32_16x16x32_bf16 v[46:49], v[146:149], v[186:189], v[46:49]
	v_mfma_f32_16x16x32_bf16 v[42:45], v[138:141], v[194:197], v[42:45]
	v_mfma_f32_16x16x32_bf16 v[38:41], v[146:149], v[194:197], v[38:41]
	s_setprio 0
	s_setprio 1
	v_mfma_f32_16x16x32_bf16 v[34:37], v[150:153], v[166:169], v[34:37]
	v_mfma_f32_16x16x32_bf16 v[30:33], v[158:161], v[166:169], v[30:33]
	v_mfma_f32_16x16x32_bf16 v[26:29], v[150:153], v[174:177], v[26:29]
	v_mfma_f32_16x16x32_bf16 v[22:25], v[158:161], v[174:177], v[22:25]
	v_mfma_f32_16x16x32_bf16 v[18:21], v[150:153], v[182:185], v[18:21]
	v_mfma_f32_16x16x32_bf16 v[14:17], v[158:161], v[182:185], v[14:17]
	v_mfma_f32_16x16x32_bf16 v[10:13], v[150:153], v[190:193], v[10:13]
	v_mfma_f32_16x16x32_bf16 v[4:7], v[158:161], v[190:193], v[6:9]
	v_mfma_f32_16x16x32_bf16 v[34:37], v[154:157], v[170:173], v[34:37]
	v_mfma_f32_16x16x32_bf16 v[30:33], v[162:165], v[170:173], v[30:33]
	v_mfma_f32_16x16x32_bf16 v[26:29], v[154:157], v[178:181], v[26:29]
	v_mfma_f32_16x16x32_bf16 v[22:25], v[162:165], v[178:181], v[22:25]
	v_mfma_f32_16x16x32_bf16 v[18:21], v[154:157], v[186:189], v[18:21]
	v_mfma_f32_16x16x32_bf16 v[14:17], v[162:165], v[186:189], v[14:17]
	v_mfma_f32_16x16x32_bf16 v[10:13], v[154:157], v[194:197], v[10:13]
	v_mfma_f32_16x16x32_bf16 v[4:7], v[162:165], v[194:197], v[4:7]
	s_setprio 0
	s_barrier
	s_add_i32 s64, 0, 0x18000
	v_add_u32_e32 v2, s64, v199
	s_add_i32 s65, 0, 0x1c000
	ds_read_b128 v[134:137], v2
	ds_read_b128 v[138:141], v2 offset:1024
	ds_read_b128 v[142:145], v2 offset:2048
	ds_read_b128 v[146:149], v2 offset:3072
	v_add_u32_e32 v2, s65, v199
	ds_read_b128 v[150:153], v2
	ds_read_b128 v[154:157], v2 offset:1024
	ds_read_b128 v[158:161], v2 offset:2048
	ds_read_b128 v[162:165], v2 offset:3072
	s_add_u32 s40, s40, s8
	s_addc_u32 s41, s41, s9
	s_mov_b32 m0, s47
	v_lshl_add_u64 v[8:9], s[40:41], 0, v[200:201]
	ds_read_b128 v[166:169], v228 offset:32768
	ds_read_b128 v[170:173], v228 offset:33792
	ds_read_b128 v[174:177], v228 offset:34816
	ds_read_b128 v[178:181], v228 offset:35840
	ds_read_b128 v[182:185], v228 offset:36864
	ds_read_b128 v[186:189], v228 offset:37888
	ds_read_b128 v[190:193], v228 offset:38912
	ds_read_b128 v[194:197], v228 offset:39936
	global_load_lds_dwordx4 v[8:9], off
	v_lshl_add_u64 v[8:9], s[40:41], 0, v[204:205]
	s_mov_b32 m0, s48
	s_nop 0
	global_load_lds_dwordx4 v[8:9], off
	s_waitcnt vmcnt(8)
	s_waitcnt lgkmcnt(0)
	s_barrier
	s_setprio 1
	s_waitcnt lgkmcnt(0)
	v_mfma_f32_16x16x32_bf16 v[130:133], v[134:137], v[166:169], v[130:133]
	v_mfma_f32_16x16x32_bf16 v[126:129], v[142:145], v[166:169], v[126:129]
	v_mfma_f32_16x16x32_bf16 v[122:125], v[134:137], v[174:177], v[122:125]
	v_mfma_f32_16x16x32_bf16 v[118:121], v[142:145], v[174:177], v[118:121]
	v_mfma_f32_16x16x32_bf16 v[114:117], v[134:137], v[182:185], v[114:117]
	v_mfma_f32_16x16x32_bf16 v[110:113], v[142:145], v[182:185], v[110:113]
	v_mfma_f32_16x16x32_bf16 v[106:109], v[134:137], v[190:193], v[106:109]
	v_mfma_f32_16x16x32_bf16 v[102:105], v[142:145], v[190:193], v[102:105]
	v_mfma_f32_16x16x32_bf16 v[130:133], v[138:141], v[170:173], v[130:133]
	v_mfma_f32_16x16x32_bf16 v[126:129], v[146:149], v[170:173], v[126:129]
	v_mfma_f32_16x16x32_bf16 v[122:125], v[138:141], v[178:181], v[122:125]
	v_mfma_f32_16x16x32_bf16 v[118:121], v[146:149], v[178:181], v[118:121]
	v_mfma_f32_16x16x32_bf16 v[114:117], v[138:141], v[186:189], v[114:117]
	v_mfma_f32_16x16x32_bf16 v[110:113], v[146:149], v[186:189], v[110:113]
	v_mfma_f32_16x16x32_bf16 v[106:109], v[138:141], v[194:197], v[106:109]
	v_mfma_f32_16x16x32_bf16 v[102:105], v[146:149], v[194:197], v[102:105]
	s_setprio 0
	s_setprio 1
	v_mfma_f32_16x16x32_bf16 v[98:101], v[150:153], v[166:169], v[98:101]
	v_mfma_f32_16x16x32_bf16 v[94:97], v[158:161], v[166:169], v[94:97]
	v_mfma_f32_16x16x32_bf16 v[90:93], v[150:153], v[174:177], v[90:93]
	v_mfma_f32_16x16x32_bf16 v[86:89], v[158:161], v[174:177], v[86:89]
	v_mfma_f32_16x16x32_bf16 v[82:85], v[150:153], v[182:185], v[82:85]
	v_mfma_f32_16x16x32_bf16 v[78:81], v[158:161], v[182:185], v[78:81]
	v_mfma_f32_16x16x32_bf16 v[74:77], v[150:153], v[190:193], v[74:77]
	v_mfma_f32_16x16x32_bf16 v[70:73], v[158:161], v[190:193], v[70:73]
	v_mfma_f32_16x16x32_bf16 v[98:101], v[154:157], v[170:173], v[98:101]
	v_mfma_f32_16x16x32_bf16 v[94:97], v[162:165], v[170:173], v[94:97]
	v_mfma_f32_16x16x32_bf16 v[90:93], v[154:157], v[178:181], v[90:93]
	v_mfma_f32_16x16x32_bf16 v[86:89], v[162:165], v[178:181], v[86:89]
	v_mfma_f32_16x16x32_bf16 v[82:85], v[154:157], v[186:189], v[82:85]
	v_mfma_f32_16x16x32_bf16 v[78:81], v[162:165], v[186:189], v[78:81]
	v_mfma_f32_16x16x32_bf16 v[74:77], v[154:157], v[194:197], v[74:77]
	v_mfma_f32_16x16x32_bf16 v[70:73], v[162:165], v[194:197], v[70:73]
	s_setprio 0
	s_barrier
	s_add_i32 s40, s64, s2
	v_lshl_add_u64 v[8:9], v[216:217], 0, s[14:15]
	s_mov_b32 m0, s40
	ds_read_b128 v[166:169], v228 offset:49152
	ds_read_b128 v[170:173], v228 offset:50176
	ds_read_b128 v[174:177], v228 offset:51200
	ds_read_b128 v[178:181], v228 offset:52224
	ds_read_b128 v[182:185], v228 offset:53248
	ds_read_b128 v[186:189], v228 offset:54272
	ds_read_b128 v[190:193], v228 offset:55296
	ds_read_b128 v[194:197], v228 offset:56320
	global_load_lds_dwordx4 v[8:9], off
	v_lshl_add_u64 v[8:9], v[218:219], 0, s[14:15]
	s_add_i32 m0, s40, 0x2000
	s_add_i32 s40, s65, s2
	global_load_lds_dwordx4 v[8:9], off
	v_lshl_add_u64 v[8:9], v[220:221], 0, s[14:15]
	s_mov_b32 m0, s40
	s_nop 0
	global_load_lds_dwordx4 v[8:9], off
	v_lshl_add_u64 v[8:9], v[222:223], 0, s[14:15]
	s_add_i32 m0, s40, 0x2000
	s_nop 0
	global_load_lds_dwordx4 v[8:9], off
	v_lshl_add_u64 v[8:9], v[230:231], 0, s[14:15]
	s_mov_b32 m0, s54
	s_nop 0
	global_load_lds_dwordx4 v[8:9], off
	v_lshl_add_u64 v[8:9], v[232:233], 0, s[14:15]
	s_mov_b32 m0, s55
	s_nop 0
	global_load_lds_dwordx4 v[8:9], off
	s_waitcnt vmcnt(8)
	s_waitcnt lgkmcnt(0)
	s_barrier
	s_setprio 1
	s_waitcnt lgkmcnt(0)
	v_mfma_f32_16x16x32_bf16 v[66:69], v[134:137], v[166:169], v[66:69]
	v_mfma_f32_16x16x32_bf16 v[62:65], v[142:145], v[166:169], v[62:65]
	v_mfma_f32_16x16x32_bf16 v[58:61], v[134:137], v[174:177], v[58:61]
	v_mfma_f32_16x16x32_bf16 v[54:57], v[142:145], v[174:177], v[54:57]
	v_mfma_f32_16x16x32_bf16 v[50:53], v[134:137], v[182:185], v[50:53]
	v_mfma_f32_16x16x32_bf16 v[46:49], v[142:145], v[182:185], v[46:49]
	v_mfma_f32_16x16x32_bf16 v[42:45], v[134:137], v[190:193], v[42:45]
	v_mfma_f32_16x16x32_bf16 v[38:41], v[142:145], v[190:193], v[38:41]
	v_mfma_f32_16x16x32_bf16 v[66:69], v[138:141], v[170:173], v[66:69]
	v_mfma_f32_16x16x32_bf16 v[62:65], v[146:149], v[170:173], v[62:65]
	v_mfma_f32_16x16x32_bf16 v[58:61], v[138:141], v[178:181], v[58:61]
	v_mfma_f32_16x16x32_bf16 v[54:57], v[146:149], v[178:181], v[54:57]
	v_mfma_f32_16x16x32_bf16 v[50:53], v[138:141], v[186:189], v[50:53]
	v_mfma_f32_16x16x32_bf16 v[46:49], v[146:149], v[186:189], v[46:49]
	v_mfma_f32_16x16x32_bf16 v[42:45], v[138:141], v[194:197], v[42:45]
	v_mfma_f32_16x16x32_bf16 v[38:41], v[146:149], v[194:197], v[38:41]
	s_setprio 0
	s_setprio 1
	v_mfma_f32_16x16x32_bf16 v[34:37], v[150:153], v[166:169], v[34:37]
	v_mfma_f32_16x16x32_bf16 v[30:33], v[158:161], v[166:169], v[30:33]
	v_mfma_f32_16x16x32_bf16 v[26:29], v[150:153], v[174:177], v[26:29]
	v_mfma_f32_16x16x32_bf16 v[22:25], v[158:161], v[174:177], v[22:25]
	v_mfma_f32_16x16x32_bf16 v[18:21], v[150:153], v[182:185], v[18:21]
	v_mfma_f32_16x16x32_bf16 v[14:17], v[158:161], v[182:185], v[14:17]
	v_mfma_f32_16x16x32_bf16 v[8:11], v[150:153], v[190:193], v[10:13]
	v_mfma_f32_16x16x32_bf16 v[4:7], v[158:161], v[190:193], v[4:7]
	v_mfma_f32_16x16x32_bf16 v[34:37], v[154:157], v[170:173], v[34:37]
	v_mfma_f32_16x16x32_bf16 v[30:33], v[162:165], v[170:173], v[30:33]
	v_mfma_f32_16x16x32_bf16 v[26:29], v[154:157], v[178:181], v[26:29]
	v_mfma_f32_16x16x32_bf16 v[22:25], v[162:165], v[178:181], v[22:25]
	v_mfma_f32_16x16x32_bf16 v[18:21], v[154:157], v[186:189], v[18:21]
	v_mfma_f32_16x16x32_bf16 v[14:17], v[162:165], v[186:189], v[14:17]
	v_mfma_f32_16x16x32_bf16 v[10:13], v[154:157], v[194:197], v[8:11]
	v_mfma_f32_16x16x32_bf16 v[6:9], v[162:165], v[194:197], v[4:7]
	s_setprio 0
	s_barrier
	s_add_u32 s38, s38, 0x100
	s_addc_u32 s39, s39, 0
	s_add_u32 s29, s29, 0x100
	s_addc_u32 s62, s62, 0
	s_cmp_ge_i32 s63, s53
	s_mov_b32 s40, s63
	s_cbranch_scc0 .LBB0_1987
	s_getpc_b64 s[98:99]
	s_mov_b32 m0, 0x22800
	v_lshlrev_b32_e32 v194, 7, v0
	global_load_lds_dword v194, s[98:99]

.LBB0_2160:
	s_waitcnt lgkmcnt(0)
	ds_read_b128 v[130:133], v220
	ds_read_b128 v[134:137], v220 offset:1024
	ds_read_b128 v[138:141], v220 offset:2048
	ds_read_b128 v[142:145], v220 offset:3072
	ds_read_b128 v[146:149], v221
	ds_read_b128 v[150:153], v221 offset:1024
	ds_read_b128 v[154:157], v221 offset:2048
	ds_read_b128 v[158:161], v221 offset:3072
	s_add_i32 s62, s42, 2
	s_add_u32 s63, s40, 0x80
	s_addc_u32 s43, s41, 0
	s_cmp_eq_u32 s54, s42
	s_cselect_b32 s42, s29, s63
	s_cselect_b32 s43, s13, s43
	s_cselect_b32 s65, s31, s61
	s_cselect_b32 s64, s59, s60
	v_lshl_add_u64 v[214:215], s[40:41], 0, v[210:211]
	s_add_i32 m0, s3, 0xc000
	ds_read_b128 v[162:165], v222
	ds_read_b128 v[166:169], v222 offset:1024
	ds_read_b128 v[170:173], v222 offset:2048
	ds_read_b128 v[174:177], v222 offset:3072
	ds_read_b128 v[178:181], v222 offset:4096
	ds_read_b128 v[182:185], v222 offset:5120
	ds_read_b128 v[186:189], v222 offset:6144
	ds_read_b128 v[190:193], v222 offset:7168
	global_load_lds_dwordx4 v[214:215], off
	v_lshl_add_u64 v[214:215], s[40:41], 0, v[212:213]
	s_add_i32 m0, s3, 0xe000
	s_nop 0
	global_load_lds_dwordx4 v[214:215], off
	s_waitcnt vmcnt(8)
	s_waitcnt lgkmcnt(0)
	s_barrier
	s_setprio 1
	s_waitcnt lgkmcnt(0)
	v_mfma_f32_16x16x32_bf16 v[118:121], v[130:133], v[162:165], v[118:121]
	v_mfma_f32_16x16x32_bf16 v[126:129], v[138:141], v[162:165], v[126:129]
	v_mfma_f32_16x16x32_bf16 v[110:113], v[130:133], v[170:173], v[110:113]
	v_mfma_f32_16x16x32_bf16 v[106:109], v[138:141], v[170:173], v[106:109]
	v_mfma_f32_16x16x32_bf16 v[94:97], v[130:133], v[178:181], v[94:97]
	v_mfma_f32_16x16x32_bf16 v[90:93], v[138:141], v[178:181], v[90:93]
	v_mfma_f32_16x16x32_bf16 v[78:81], v[130:133], v[186:189], v[78:81]
	v_mfma_f32_16x16x32_bf16 v[74:77], v[138:141], v[186:189], v[74:77]
	v_mfma_f32_16x16x32_bf16 v[118:121], v[134:137], v[166:169], v[118:121]
	v_mfma_f32_16x16x32_bf16 v[126:129], v[142:145], v[166:169], v[126:129]
	v_mfma_f32_16x16x32_bf16 v[110:113], v[134:137], v[174:177], v[110:113]
	v_mfma_f32_16x16x32_bf16 v[106:109], v[142:145], v[174:177], v[106:109]
	v_mfma_f32_16x16x32_bf16 v[94:97], v[134:137], v[182:185], v[94:97]
	v_mfma_f32_16x16x32_bf16 v[90:93], v[142:145], v[182:185], v[90:93]
	v_mfma_f32_16x16x32_bf16 v[78:81], v[134:137], v[190:193], v[78:81]
	v_mfma_f32_16x16x32_bf16 v[74:77], v[142:145], v[190:193], v[74:77]
	s_setprio 0
	s_setprio 1
	v_mfma_f32_16x16x32_bf16 v[122:125], v[146:149], v[162:165], v[122:125]
	v_mfma_f32_16x16x32_bf16 v[114:117], v[154:157], v[162:165], v[114:117]
	v_mfma_f32_16x16x32_bf16 v[102:105], v[146:149], v[170:173], v[102:105]
	v_mfma_f32_16x16x32_bf16 v[98:101], v[154:157], v[170:173], v[98:101]
	v_mfma_f32_16x16x32_bf16 v[86:89], v[146:149], v[178:181], v[86:89]
	v_mfma_f32_16x16x32_bf16 v[82:85], v[154:157], v[178:181], v[82:85]
	v_mfma_f32_16x16x32_bf16 v[70:73], v[146:149], v[186:189], v[70:73]
	v_mfma_f32_16x16x32_bf16 v[66:69], v[154:157], v[186:189], v[66:69]
	v_mfma_f32_16x16x32_bf16 v[122:125], v[150:153], v[166:169], v[122:125]
	v_mfma_f32_16x16x32_bf16 v[114:117], v[158:161], v[166:169], v[114:117]
	v_mfma_f32_16x16x32_bf16 v[102:105], v[150:153], v[174:177], v[102:105]
	v_mfma_f32_16x16x32_bf16 v[98:101], v[158:161], v[174:177], v[98:101]
	v_mfma_f32_16x16x32_bf16 v[86:89], v[150:153], v[182:185], v[86:89]
	v_mfma_f32_16x16x32_bf16 v[82:85], v[158:161], v[182:185], v[82:85]
	v_mfma_f32_16x16x32_bf16 v[70:73], v[150:153], v[190:193], v[70:73]
	v_mfma_f32_16x16x32_bf16 v[66:69], v[158:161], v[190:193], v[66:69]
	s_setprio 0
	s_barrier
	s_add_i32 s63, s55, s2
	v_lshl_add_u64 v[214:215], s[64:65], 0, v[196:197]
	s_mov_b32 m0, s63
	ds_read_b128 v[162:165], v222 offset:16384
	ds_read_b128 v[166:169], v222 offset:17408
	ds_read_b128 v[170:173], v222 offset:18432
	ds_read_b128 v[174:177], v222 offset:19456
	ds_read_b128 v[178:181], v222 offset:20480
	ds_read_b128 v[182:185], v222 offset:21504
	ds_read_b128 v[186:189], v222 offset:22528
	ds_read_b128 v[190:193], v222 offset:23552
	global_load_lds_dwordx4 v[214:215], off
	s_add_i32 m0, s63, 0x2000
	v_lshl_add_u64 v[216:217], s[64:65], 0, v[202:203]
	s_add_u32 s64, s64, s14
	s_addc_u32 s65, s65, s15
	s_add_i32 s63, s56, s2
	global_load_lds_dwordx4 v[216:217], off
	v_lshl_add_u64 v[224:225], s[64:65], 0, v[196:197]
	s_mov_b32 m0, s63
	v_lshl_add_u64 v[226:227], s[64:65], 0, v[202:203]
	global_load_lds_dwordx4 v[224:225], off
	s_add_i32 m0, s63, 0x2000
	v_lshl_add_u64 v[228:229], s[42:43], 0, v[194:195]
	global_load_lds_dwordx4 v[226:227], off
	s_mov_b32 m0, s3
	v_lshl_add_u64 v[230:231], s[42:43], 0, v[200:201]
	global_load_lds_dwordx4 v[228:229], off
	s_mov_b32 m0, s47
	s_nop 0
	global_load_lds_dwordx4 v[230:231], off
	s_waitcnt vmcnt(8)
	s_waitcnt lgkmcnt(0)
	s_barrier
	s_setprio 1
	s_waitcnt lgkmcnt(0)
	v_mfma_f32_16x16x32_bf16 v[62:65], v[130:133], v[162:165], v[62:65]
	v_mfma_f32_16x16x32_bf16 v[58:61], v[138:141], v[162:165], v[58:61]
	v_mfma_f32_16x16x32_bf16 v[46:49], v[130:133], v[170:173], v[46:49]
	v_mfma_f32_16x16x32_bf16 v[42:45], v[138:141], v[170:173], v[42:45]
	v_mfma_f32_16x16x32_bf16 v[30:33], v[130:133], v[178:181], v[30:33]
	v_mfma_f32_16x16x32_bf16 v[26:29], v[138:141], v[178:181], v[26:29]
	v_mfma_f32_16x16x32_bf16 v[14:17], v[130:133], v[186:189], v[14:17]
	v_mfma_f32_16x16x32_bf16 v[10:13], v[138:141], v[186:189], v[10:13]
	v_mfma_f32_16x16x32_bf16 v[62:65], v[134:137], v[166:169], v[62:65]
	v_mfma_f32_16x16x32_bf16 v[58:61], v[142:145], v[166:169], v[58:61]
	v_mfma_f32_16x16x32_bf16 v[46:49], v[134:137], v[174:177], v[46:49]
	v_mfma_f32_16x16x32_bf16 v[42:45], v[142:145], v[174:177], v[42:45]
	v_mfma_f32_16x16x32_bf16 v[30:33], v[134:137], v[182:185], v[30:33]
	v_mfma_f32_16x16x32_bf16 v[26:29], v[142:145], v[182:185], v[26:29]
	v_mfma_f32_16x16x32_bf16 v[14:17], v[134:137], v[190:193], v[14:17]
	v_mfma_f32_16x16x32_bf16 v[10:13], v[142:145], v[190:193], v[10:13]
	s_setprio 0
	s_setprio 1
	v_mfma_f32_16x16x32_bf16 v[54:57], v[146:149], v[162:165], v[54:57]
	v_mfma_f32_16x16x32_bf16 v[50:53], v[154:157], v[162:165], v[50:53]
	v_mfma_f32_16x16x32_bf16 v[38:41], v[146:149], v[170:173], v[38:41]
	v_mfma_f32_16x16x32_bf16 v[34:37], v[154:157], v[170:173], v[34:37]
	v_mfma_f32_16x16x32_bf16 v[22:25], v[146:149], v[178:181], v[22:25]
	v_mfma_f32_16x16x32_bf16 v[18:21], v[154:157], v[178:181], v[18:21]
	v_mfma_f32_16x16x32_bf16 v[6:9], v[146:149], v[186:189], v[6:9]
	v_mfma_f32_16x16x32_bf16 v[2:5], v[154:157], v[186:189], v[2:5]
	v_mfma_f32_16x16x32_bf16 v[54:57], v[150:153], v[166:169], v[54:57]
	v_mfma_f32_16x16x32_bf16 v[50:53], v[158:161], v[166:169], v[50:53]
	v_mfma_f32_16x16x32_bf16 v[38:41], v[150:153], v[174:177], v[38:41]
	v_mfma_f32_16x16x32_bf16 v[34:37], v[158:161], v[174:177], v[34:37]
	v_mfma_f32_16x16x32_bf16 v[22:25], v[150:153], v[182:185], v[22:25]
	v_mfma_f32_16x16x32_bf16 v[18:21], v[158:161], v[182:185], v[18:21]
	v_mfma_f32_16x16x32_bf16 v[6:9], v[150:153], v[190:193], v[6:9]
	v_mfma_f32_16x16x32_bf16 v[2:5], v[158:161], v[190:193], v[2:5]
	s_setprio 0
	s_barrier
	s_add_i32 s63, 0, 0x18000
	s_add_i32 s64, 0, 0x1c000
	v_add_u32_e32 v142, s63, v199
	v_add_u32_e32 v158, s64, v199
	ds_read_b128 v[130:133], v142
	ds_read_b128 v[134:137], v142 offset:1024
	ds_read_b128 v[138:141], v142 offset:2048
	ds_read_b128 v[142:145], v142 offset:3072
	ds_read_b128 v[146:149], v158
	ds_read_b128 v[150:153], v158 offset:1024
	ds_read_b128 v[154:157], v158 offset:2048
	ds_read_b128 v[158:161], v158 offset:3072
	s_add_u32 s42, s42, s14
	s_addc_u32 s43, s43, s15
	s_mov_b32 m0, s48
	v_lshl_add_u64 v[232:233], s[42:43], 0, v[194:195]
	ds_read_b128 v[162:165], v222 offset:32768
	ds_read_b128 v[166:169], v222 offset:33792
	ds_read_b128 v[170:173], v222 offset:34816
	ds_read_b128 v[174:177], v222 offset:35840
	ds_read_b128 v[178:181], v222 offset:36864
	ds_read_b128 v[182:185], v222 offset:37888
	ds_read_b128 v[186:189], v222 offset:38912
	ds_read_b128 v[190:193], v222 offset:39936
	global_load_lds_dwordx4 v[232:233], off
	v_lshl_add_u64 v[232:233], s[42:43], 0, v[200:201]
	s_mov_b32 m0, s49
	s_nop 0
	global_load_lds_dwordx4 v[232:233], off
	s_waitcnt vmcnt(8)
	s_waitcnt lgkmcnt(0)
	s_barrier
	s_setprio 1
	s_waitcnt lgkmcnt(0)
	v_mfma_f32_16x16x32_bf16 v[118:121], v[130:133], v[162:165], v[118:121]
	v_mfma_f32_16x16x32_bf16 v[126:129], v[138:141], v[162:165], v[126:129]
	v_mfma_f32_16x16x32_bf16 v[110:113], v[130:133], v[170:173], v[110:113]
	v_mfma_f32_16x16x32_bf16 v[106:109], v[138:141], v[170:173], v[106:109]
	v_mfma_f32_16x16x32_bf16 v[94:97], v[130:133], v[178:181], v[94:97]
	v_mfma_f32_16x16x32_bf16 v[90:93], v[138:141], v[178:181], v[90:93]
	v_mfma_f32_16x16x32_bf16 v[78:81], v[130:133], v[186:189], v[78:81]
	v_mfma_f32_16x16x32_bf16 v[74:77], v[138:141], v[186:189], v[74:77]
	v_mfma_f32_16x16x32_bf16 v[118:121], v[134:137], v[166:169], v[118:121]
	v_mfma_f32_16x16x32_bf16 v[126:129], v[142:145], v[166:169], v[126:129]
	v_mfma_f32_16x16x32_bf16 v[110:113], v[134:137], v[174:177], v[110:113]
	v_mfma_f32_16x16x32_bf16 v[106:109], v[142:145], v[174:177], v[106:109]
	v_mfma_f32_16x16x32_bf16 v[94:97], v[134:137], v[182:185], v[94:97]
	v_mfma_f32_16x16x32_bf16 v[90:93], v[142:145], v[182:185], v[90:93]
	v_mfma_f32_16x16x32_bf16 v[78:81], v[134:137], v[190:193], v[78:81]
	v_mfma_f32_16x16x32_bf16 v[74:77], v[142:145], v[190:193], v[74:77]
	s_setprio 0
	s_setprio 1
	v_mfma_f32_16x16x32_bf16 v[122:125], v[146:149], v[162:165], v[122:125]
	v_mfma_f32_16x16x32_bf16 v[114:117], v[154:157], v[162:165], v[114:117]
	v_mfma_f32_16x16x32_bf16 v[102:105], v[146:149], v[170:173], v[102:105]
	v_mfma_f32_16x16x32_bf16 v[98:101], v[154:157], v[170:173], v[98:101]
	v_mfma_f32_16x16x32_bf16 v[86:89], v[146:149], v[178:181], v[86:89]
	v_mfma_f32_16x16x32_bf16 v[82:85], v[154:157], v[178:181], v[82:85]
	v_mfma_f32_16x16x32_bf16 v[70:73], v[146:149], v[186:189], v[70:73]
	v_mfma_f32_16x16x32_bf16 v[66:69], v[154:157], v[186:189], v[66:69]
	v_mfma_f32_16x16x32_bf16 v[122:125], v[150:153], v[166:169], v[122:125]
	v_mfma_f32_16x16x32_bf16 v[114:117], v[158:161], v[166:169], v[114:117]
	v_mfma_f32_16x16x32_bf16 v[102:105], v[150:153], v[174:177], v[102:105]
	v_mfma_f32_16x16x32_bf16 v[98:101], v[158:161], v[174:177], v[98:101]
	v_mfma_f32_16x16x32_bf16 v[86:89], v[150:153], v[182:185], v[86:89]
	v_mfma_f32_16x16x32_bf16 v[82:85], v[158:161], v[182:185], v[82:85]
	v_mfma_f32_16x16x32_bf16 v[70:73], v[150:153], v[190:193], v[70:73]
	v_mfma_f32_16x16x32_bf16 v[66:69], v[158:161], v[190:193], v[66:69]
	s_setprio 0
	s_barrier
	s_add_i32 s42, s63, s2
	v_lshl_add_u64 v[214:215], v[214:215], 0, s[20:21]
	s_mov_b32 m0, s42
	ds_read_b128 v[162:165], v222 offset:49152
	ds_read_b128 v[166:169], v222 offset:50176
	ds_read_b128 v[170:173], v222 offset:51200
	ds_read_b128 v[174:177], v222 offset:52224
	ds_read_b128 v[178:181], v222 offset:53248
	ds_read_b128 v[182:185], v222 offset:54272
	ds_read_b128 v[186:189], v222 offset:55296
	ds_read_b128 v[190:193], v222 offset:56320
	global_load_lds_dwordx4 v[214:215], off
	v_lshl_add_u64 v[214:215], v[216:217], 0, s[20:21]
	s_add_i32 m0, s42, 0x2000
	s_add_i32 s42, s64, s2
	global_load_lds_dwordx4 v[214:215], off
	v_lshl_add_u64 v[214:215], v[224:225], 0, s[20:21]
	s_mov_b32 m0, s42
	s_nop 0
	global_load_lds_dwordx4 v[214:215], off
	v_lshl_add_u64 v[214:215], v[226:227], 0, s[20:21]
	s_add_i32 m0, s42, 0x2000
	s_nop 0
	global_load_lds_dwordx4 v[214:215], off
	v_lshl_add_u64 v[214:215], v[228:229], 0, s[20:21]
	s_mov_b32 m0, s50
	s_nop 0
	global_load_lds_dwordx4 v[214:215], off
	v_lshl_add_u64 v[214:215], v[230:231], 0, s[20:21]
	s_mov_b32 m0, s51
	s_nop 0
	global_load_lds_dwordx4 v[214:215], off
	s_waitcnt vmcnt(8)
	s_waitcnt lgkmcnt(0)
	s_barrier
	s_setprio 1
	s_waitcnt lgkmcnt(0)
	v_mfma_f32_16x16x32_bf16 v[62:65], v[130:133], v[162:165], v[62:65]
	v_mfma_f32_16x16x32_bf16 v[58:61], v[138:141], v[162:165], v[58:61]
	v_mfma_f32_16x16x32_bf16 v[46:49], v[130:133], v[170:173], v[46:49]
	v_mfma_f32_16x16x32_bf16 v[42:45], v[138:141], v[170:173], v[42:45]
	v_mfma_f32_16x16x32_bf16 v[30:33], v[130:133], v[178:181], v[30:33]
	v_mfma_f32_16x16x32_bf16 v[26:29], v[138:141], v[178:181], v[26:29]
	v_mfma_f32_16x16x32_bf16 v[14:17], v[130:133], v[186:189], v[14:17]
	v_mfma_f32_16x16x32_bf16 v[10:13], v[138:141], v[186:189], v[10:13]
	v_mfma_f32_16x16x32_bf16 v[62:65], v[134:137], v[166:169], v[62:65]
	v_mfma_f32_16x16x32_bf16 v[58:61], v[142:145], v[166:169], v[58:61]
	v_mfma_f32_16x16x32_bf16 v[46:49], v[134:137], v[174:177], v[46:49]
	v_mfma_f32_16x16x32_bf16 v[42:45], v[142:145], v[174:177], v[42:45]
	v_mfma_f32_16x16x32_bf16 v[30:33], v[134:137], v[182:185], v[30:33]
	v_mfma_f32_16x16x32_bf16 v[26:29], v[142:145], v[182:185], v[26:29]
	v_mfma_f32_16x16x32_bf16 v[14:17], v[134:137], v[190:193], v[14:17]
	v_mfma_f32_16x16x32_bf16 v[10:13], v[142:145], v[190:193], v[10:13]
	s_setprio 0
	s_setprio 1
	v_mfma_f32_16x16x32_bf16 v[54:57], v[146:149], v[162:165], v[54:57]
	v_mfma_f32_16x16x32_bf16 v[50:53], v[154:157], v[162:165], v[50:53]
	v_mfma_f32_16x16x32_bf16 v[38:41], v[146:149], v[170:173], v[38:41]
	v_mfma_f32_16x16x32_bf16 v[34:37], v[154:157], v[170:173], v[34:37]
	v_mfma_f32_16x16x32_bf16 v[22:25], v[146:149], v[178:181], v[22:25]
	v_mfma_f32_16x16x32_bf16 v[18:21], v[154:157], v[178:181], v[18:21]
	v_mfma_f32_16x16x32_bf16 v[6:9], v[146:149], v[186:189], v[6:9]
	v_mfma_f32_16x16x32_bf16 v[2:5], v[154:157], v[186:189], v[2:5]
	v_mfma_f32_16x16x32_bf16 v[54:57], v[150:153], v[166:169], v[54:57]
	v_mfma_f32_16x16x32_bf16 v[50:53], v[158:161], v[166:169], v[50:53]
	v_mfma_f32_16x16x32_bf16 v[38:41], v[150:153], v[174:177], v[38:41]
	v_mfma_f32_16x16x32_bf16 v[34:37], v[158:161], v[174:177], v[34:37]
	v_mfma_f32_16x16x32_bf16 v[22:25], v[150:153], v[182:185], v[22:25]
	v_mfma_f32_16x16x32_bf16 v[18:21], v[158:161], v[182:185], v[18:21]
	v_mfma_f32_16x16x32_bf16 v[6:9], v[150:153], v[190:193], v[6:9]
	v_mfma_f32_16x16x32_bf16 v[2:5], v[158:161], v[190:193], v[2:5]
	s_setprio 0
	s_barrier
	s_add_u32 s40, s40, 0x100
	s_addc_u32 s41, s41, 0
	s_add_u32 s60, s60, 0x100
	s_addc_u32 s61, s61, 0
	s_cmp_ge_i32 s62, s53
	s_mov_b32 s42, s62
	s_cbranch_scc0 .LBB0_2160
	s_getpc_b64 s[98:99]
	s_mov_b32 m0, 0x22800
	v_lshlrev_b32_e32 v190, 7, v0
	global_load_lds_dword v190, s[98:99]

.LBB0_2194:
	v_add_u32_e32 v103, s53, v146
	ds_read_b128 v[148:151], v103
	ds_read_b128 v[152:155], v103 offset:1024
	ds_read_b128 v[156:159], v103 offset:2048
	ds_read_b128 v[160:163], v103 offset:3072
	v_add_u32_e32 v103, s54, v146
	ds_read_b128 v[164:167], v103
	ds_read_b128 v[168:171], v103 offset:1024
	ds_read_b128 v[172:175], v103 offset:2048
	ds_read_b128 v[176:179], v103 offset:3072
	s_add_i32 s63, s36, 2
	s_add_u32 s64, s34, 0x80
	s_addc_u32 s37, s35, 0
	s_cmp_eq_u32 s52, s36
	s_cselect_b32 s36, s23, s64
	s_cselect_b32 s37, s21, s37
	s_cselect_b32 s65, s59, s62
	s_cselect_b32 s64, s60, s61
	s_mov_b32 m0, s55
	v_lshl_add_u64 v[104:105], s[34:35], 0, v[142:143]
	ds_read_b128 v[180:183], v147
	ds_read_b128 v[184:187], v147 offset:1024
	ds_read_b128 v[188:191], v147 offset:2048
	ds_read_b128 v[192:195], v147 offset:3072
	ds_read_b128 v[200:203], v147 offset:4096
	ds_read_b128 v[204:207], v147 offset:5120
	ds_read_b128 v[208:211], v147 offset:6144
	ds_read_b128 v[212:215], v147 offset:7168
	global_load_lds_dwordx4 v[104:105], off
	v_lshl_add_u64 v[104:105], s[34:35], 0, v[144:145]
	s_mov_b32 m0, s56
	s_nop 0
	global_load_lds_dwordx4 v[104:105], off
	s_waitcnt vmcnt(8)
	s_waitcnt lgkmcnt(0)
	s_barrier
	s_setprio 1
	s_waitcnt lgkmcnt(0)
	v_mfma_f32_16x16x32_bf16 v[130:133], v[148:151], v[180:183], v[130:133]
	v_mfma_f32_16x16x32_bf16 v[126:129], v[156:159], v[180:183], v[126:129]
	v_mfma_f32_16x16x32_bf16 v[114:117], v[148:151], v[188:191], v[114:117]
	v_mfma_f32_16x16x32_bf16 v[110:113], v[156:159], v[188:191], v[110:113]
	v_mfma_f32_16x16x32_bf16 v[94:97], v[148:151], v[200:203], v[94:97]
	v_mfma_f32_16x16x32_bf16 v[90:93], v[156:159], v[200:203], v[90:93]
	v_mfma_f32_16x16x32_bf16 v[78:81], v[148:151], v[208:211], v[78:81]
	v_mfma_f32_16x16x32_bf16 v[74:77], v[156:159], v[208:211], v[74:77]
	v_mfma_f32_16x16x32_bf16 v[130:133], v[152:155], v[184:187], v[130:133]
	v_mfma_f32_16x16x32_bf16 v[126:129], v[160:163], v[184:187], v[126:129]
	v_mfma_f32_16x16x32_bf16 v[114:117], v[152:155], v[192:195], v[114:117]
	v_mfma_f32_16x16x32_bf16 v[110:113], v[160:163], v[192:195], v[110:113]
	v_mfma_f32_16x16x32_bf16 v[94:97], v[152:155], v[204:207], v[94:97]
	v_mfma_f32_16x16x32_bf16 v[90:93], v[160:163], v[204:207], v[90:93]
	v_mfma_f32_16x16x32_bf16 v[78:81], v[152:155], v[212:215], v[78:81]
	v_mfma_f32_16x16x32_bf16 v[74:77], v[160:163], v[212:215], v[74:77]
	s_setprio 0
	s_setprio 1
	v_mfma_f32_16x16x32_bf16 v[122:125], v[164:167], v[180:183], v[122:125]
	v_mfma_f32_16x16x32_bf16 v[118:121], v[172:175], v[180:183], v[118:121]
	v_mfma_f32_16x16x32_bf16 v[104:107], v[164:167], v[188:191], v[106:109]
	v_mfma_f32_16x16x32_bf16 v[98:101], v[172:175], v[188:191], v[98:101]
	v_mfma_f32_16x16x32_bf16 v[86:89], v[164:167], v[200:203], v[86:89]
	v_mfma_f32_16x16x32_bf16 v[82:85], v[172:175], v[200:203], v[82:85]
	v_mfma_f32_16x16x32_bf16 v[70:73], v[164:167], v[208:211], v[70:73]
	v_mfma_f32_16x16x32_bf16 v[66:69], v[172:175], v[208:211], v[66:69]
	v_mfma_f32_16x16x32_bf16 v[122:125], v[168:171], v[184:187], v[122:125]
	v_mfma_f32_16x16x32_bf16 v[118:121], v[176:179], v[184:187], v[118:121]
	v_mfma_f32_16x16x32_bf16 v[104:107], v[168:171], v[192:195], v[104:107]
	v_mfma_f32_16x16x32_bf16 v[98:101], v[176:179], v[192:195], v[98:101]
	v_mfma_f32_16x16x32_bf16 v[86:89], v[168:171], v[204:207], v[86:89]
	v_mfma_f32_16x16x32_bf16 v[82:85], v[176:179], v[204:207], v[82:85]
	v_mfma_f32_16x16x32_bf16 v[70:73], v[168:171], v[212:215], v[70:73]
	v_mfma_f32_16x16x32_bf16 v[66:69], v[176:179], v[212:215], v[66:69]
	s_setprio 0
	s_barrier
	s_add_i32 s66, s53, s39
	v_lshl_add_u64 v[196:197], s[64:65], 0, v[138:139]
	s_mov_b32 m0, s66
	ds_read_b128 v[180:183], v147 offset:16384
	ds_read_b128 v[184:187], v147 offset:17408
	ds_read_b128 v[188:191], v147 offset:18432
	ds_read_b128 v[192:195], v147 offset:19456
	ds_read_b128 v[200:203], v147 offset:20480
	ds_read_b128 v[204:207], v147 offset:21504
	ds_read_b128 v[208:211], v147 offset:22528
	ds_read_b128 v[212:215], v147 offset:23552
	global_load_lds_dwordx4 v[196:197], off
	s_add_i32 m0, s66, 0x2000
	v_lshl_add_u64 v[216:217], s[64:65], 0, v[134:135]
	s_add_u32 s64, s64, s0
	s_addc_u32 s65, s65, s1
	s_add_i32 s66, s54, s39
	global_load_lds_dwordx4 v[216:217], off
	v_lshl_add_u64 v[218:219], s[64:65], 0, v[138:139]
	s_mov_b32 m0, s66
	v_lshl_add_u64 v[220:221], s[64:65], 0, v[134:135]
	global_load_lds_dwordx4 v[218:219], off
	s_add_i32 m0, s66, 0x2000
	v_lshl_add_u64 v[222:223], s[36:37], 0, v[140:141]
	global_load_lds_dwordx4 v[220:221], off
	s_mov_b32 m0, s40
	v_lshl_add_u64 v[224:225], s[36:37], 0, v[136:137]
	global_load_lds_dwordx4 v[222:223], off
	s_mov_b32 m0, s41
	s_nop 0
	global_load_lds_dwordx4 v[224:225], off
	s_waitcnt vmcnt(8)
	s_waitcnt lgkmcnt(0)
	s_barrier
	s_setprio 1
	s_waitcnt lgkmcnt(0)
	v_mfma_f32_16x16x32_bf16 v[62:65], v[148:151], v[180:183], v[62:65]
	v_mfma_f32_16x16x32_bf16 v[58:61], v[156:159], v[180:183], v[58:61]
	v_mfma_f32_16x16x32_bf16 v[46:49], v[148:151], v[188:191], v[46:49]
	v_mfma_f32_16x16x32_bf16 v[42:45], v[156:159], v[188:191], v[42:45]
	v_mfma_f32_16x16x32_bf16 v[30:33], v[148:151], v[200:203], v[30:33]
	v_mfma_f32_16x16x32_bf16 v[26:29], v[156:159], v[200:203], v[26:29]
	v_mfma_f32_16x16x32_bf16 v[14:17], v[148:151], v[208:211], v[14:17]
	v_mfma_f32_16x16x32_bf16 v[10:13], v[156:159], v[208:211], v[10:13]
	v_mfma_f32_16x16x32_bf16 v[62:65], v[152:155], v[184:187], v[62:65]
	v_mfma_f32_16x16x32_bf16 v[58:61], v[160:163], v[184:187], v[58:61]
	v_mfma_f32_16x16x32_bf16 v[46:49], v[152:155], v[192:195], v[46:49]
	v_mfma_f32_16x16x32_bf16 v[42:45], v[160:163], v[192:195], v[42:45]
	v_mfma_f32_16x16x32_bf16 v[30:33], v[152:155], v[204:207], v[30:33]
	v_mfma_f32_16x16x32_bf16 v[26:29], v[160:163], v[204:207], v[26:29]
	v_mfma_f32_16x16x32_bf16 v[14:17], v[152:155], v[212:215], v[14:17]
	v_mfma_f32_16x16x32_bf16 v[10:13], v[160:163], v[212:215], v[10:13]
	s_setprio 0
	s_setprio 1
	v_mfma_f32_16x16x32_bf16 v[54:57], v[164:167], v[180:183], v[54:57]
	v_mfma_f32_16x16x32_bf16 v[50:53], v[172:175], v[180:183], v[50:53]
	v_mfma_f32_16x16x32_bf16 v[38:41], v[164:167], v[188:191], v[38:41]
	v_mfma_f32_16x16x32_bf16 v[34:37], v[172:175], v[188:191], v[34:37]
	v_mfma_f32_16x16x32_bf16 v[22:25], v[164:167], v[200:203], v[22:25]
	v_mfma_f32_16x16x32_bf16 v[18:21], v[172:175], v[200:203], v[18:21]
	v_mfma_f32_16x16x32_bf16 v[6:9], v[164:167], v[208:211], v[6:9]
	v_mfma_f32_16x16x32_bf16 v[2:5], v[172:175], v[208:211], v[2:5]
	v_mfma_f32_16x16x32_bf16 v[54:57], v[168:171], v[184:187], v[54:57]
	v_mfma_f32_16x16x32_bf16 v[50:53], v[176:179], v[184:187], v[50:53]
	v_mfma_f32_16x16x32_bf16 v[38:41], v[168:171], v[192:195], v[38:41]
	v_mfma_f32_16x16x32_bf16 v[34:37], v[176:179], v[192:195], v[34:37]
	v_mfma_f32_16x16x32_bf16 v[22:25], v[168:171], v[204:207], v[22:25]
	v_mfma_f32_16x16x32_bf16 v[18:21], v[176:179], v[204:207], v[18:21]
	v_mfma_f32_16x16x32_bf16 v[6:9], v[168:171], v[212:215], v[6:9]
	v_mfma_f32_16x16x32_bf16 v[2:5], v[176:179], v[212:215], v[2:5]
	s_setprio 0
	s_barrier
	s_add_i32 s64, 0, 0x18000
	v_add_u32_e32 v103, s64, v146
	s_add_i32 s65, 0, 0x1c000
	ds_read_b128 v[148:151], v103
	ds_read_b128 v[152:155], v103 offset:1024
	ds_read_b128 v[156:159], v103 offset:2048
	ds_read_b128 v[160:163], v103 offset:3072
	v_add_u32_e32 v103, s65, v146
	ds_read_b128 v[164:167], v103
	ds_read_b128 v[168:171], v103 offset:1024
	ds_read_b128 v[172:175], v103 offset:2048
	ds_read_b128 v[176:179], v103 offset:3072
	s_add_u32 s36, s36, s0
	s_addc_u32 s37, s37, s1
	s_mov_b32 m0, s43
	v_lshl_add_u64 v[108:109], s[36:37], 0, v[140:141]
	ds_read_b128 v[180:183], v147 offset:32768
	ds_read_b128 v[184:187], v147 offset:33792
	ds_read_b128 v[188:191], v147 offset:34816
	ds_read_b128 v[192:195], v147 offset:35840
	ds_read_b128 v[200:203], v147 offset:36864
	ds_read_b128 v[204:207], v147 offset:37888
	ds_read_b128 v[208:211], v147 offset:38912
	ds_read_b128 v[212:215], v147 offset:39936
	global_load_lds_dwordx4 v[108:109], off
	v_lshl_add_u64 v[108:109], s[36:37], 0, v[136:137]
	s_mov_b32 m0, s47
	s_nop 0
	global_load_lds_dwordx4 v[108:109], off
	s_waitcnt vmcnt(8)
	s_waitcnt lgkmcnt(0)
	s_barrier
	s_setprio 1
	s_waitcnt lgkmcnt(0)
	v_mfma_f32_16x16x32_bf16 v[130:133], v[148:151], v[180:183], v[130:133]
	v_mfma_f32_16x16x32_bf16 v[126:129], v[156:159], v[180:183], v[126:129]
	v_mfma_f32_16x16x32_bf16 v[114:117], v[148:151], v[188:191], v[114:117]
	v_mfma_f32_16x16x32_bf16 v[108:111], v[156:159], v[188:191], v[110:113]
	v_mfma_f32_16x16x32_bf16 v[94:97], v[148:151], v[200:203], v[94:97]
	v_mfma_f32_16x16x32_bf16 v[90:93], v[156:159], v[200:203], v[90:93]
	v_mfma_f32_16x16x32_bf16 v[78:81], v[148:151], v[208:211], v[78:81]
	v_mfma_f32_16x16x32_bf16 v[74:77], v[156:159], v[208:211], v[74:77]
	v_mfma_f32_16x16x32_bf16 v[130:133], v[152:155], v[184:187], v[130:133]
	v_mfma_f32_16x16x32_bf16 v[126:129], v[160:163], v[184:187], v[126:129]
	v_mfma_f32_16x16x32_bf16 v[114:117], v[152:155], v[192:195], v[114:117]
	v_mfma_f32_16x16x32_bf16 v[110:113], v[160:163], v[192:195], v[108:111]
	v_mfma_f32_16x16x32_bf16 v[94:97], v[152:155], v[204:207], v[94:97]
	v_mfma_f32_16x16x32_bf16 v[90:93], v[160:163], v[204:207], v[90:93]
	v_mfma_f32_16x16x32_bf16 v[78:81], v[152:155], v[212:215], v[78:81]
	v_mfma_f32_16x16x32_bf16 v[74:77], v[160:163], v[212:215], v[74:77]
	s_setprio 0
	s_setprio 1
	v_mfma_f32_16x16x32_bf16 v[122:125], v[164:167], v[180:183], v[122:125]
	v_mfma_f32_16x16x32_bf16 v[118:121], v[172:175], v[180:183], v[118:121]
	v_mfma_f32_16x16x32_bf16 v[104:107], v[164:167], v[188:191], v[104:107]
	v_mfma_f32_16x16x32_bf16 v[98:101], v[172:175], v[188:191], v[98:101]
	v_mfma_f32_16x16x32_bf16 v[86:89], v[164:167], v[200:203], v[86:89]
	v_mfma_f32_16x16x32_bf16 v[82:85], v[172:175], v[200:203], v[82:85]
	v_mfma_f32_16x16x32_bf16 v[70:73], v[164:167], v[208:211], v[70:73]
	v_mfma_f32_16x16x32_bf16 v[66:69], v[172:175], v[208:211], v[66:69]
	v_mfma_f32_16x16x32_bf16 v[122:125], v[168:171], v[184:187], v[122:125]
	v_mfma_f32_16x16x32_bf16 v[118:121], v[176:179], v[184:187], v[118:121]
	v_mfma_f32_16x16x32_bf16 v[106:109], v[168:171], v[192:195], v[104:107]
	v_mfma_f32_16x16x32_bf16 v[98:101], v[176:179], v[192:195], v[98:101]
	v_mfma_f32_16x16x32_bf16 v[86:89], v[168:171], v[204:207], v[86:89]
	v_mfma_f32_16x16x32_bf16 v[82:85], v[176:179], v[204:207], v[82:85]
	v_mfma_f32_16x16x32_bf16 v[70:73], v[168:171], v[212:215], v[70:73]
	v_mfma_f32_16x16x32_bf16 v[66:69], v[176:179], v[212:215], v[66:69]
	s_setprio 0
	s_barrier
	s_add_i32 s36, s64, s39
	v_lshl_add_u64 v[104:105], v[196:197], 0, s[16:17]
	s_mov_b32 m0, s36
	ds_read_b128 v[180:183], v147 offset:49152
	ds_read_b128 v[184:187], v147 offset:50176
	ds_read_b128 v[188:191], v147 offset:51200
	ds_read_b128 v[192:195], v147 offset:52224
	ds_read_b128 v[200:203], v147 offset:53248
	ds_read_b128 v[204:207], v147 offset:54272
	ds_read_b128 v[208:211], v147 offset:55296
	ds_read_b128 v[212:215], v147 offset:56320
	global_load_lds_dwordx4 v[104:105], off
	v_lshl_add_u64 v[104:105], v[216:217], 0, s[16:17]
	s_add_i32 m0, s36, 0x2000
	s_add_i32 s36, s65, s39
	global_load_lds_dwordx4 v[104:105], off
	v_lshl_add_u64 v[104:105], v[218:219], 0, s[16:17]
	s_mov_b32 m0, s36
	s_nop 0
	global_load_lds_dwordx4 v[104:105], off
	v_lshl_add_u64 v[104:105], v[220:221], 0, s[16:17]
	s_add_i32 m0, s36, 0x2000
	s_nop 0
	global_load_lds_dwordx4 v[104:105], off
	v_lshl_add_u64 v[104:105], v[222:223], 0, s[16:17]
	s_mov_b32 m0, s49
	s_nop 0
	global_load_lds_dwordx4 v[104:105], off
	v_lshl_add_u64 v[104:105], v[224:225], 0, s[16:17]
	s_mov_b32 m0, s50
	s_nop 0
	global_load_lds_dwordx4 v[104:105], off
	s_waitcnt vmcnt(8)
	s_waitcnt lgkmcnt(0)
	s_barrier
	s_setprio 1
	s_waitcnt lgkmcnt(0)
	v_mfma_f32_16x16x32_bf16 v[62:65], v[148:151], v[180:183], v[62:65]
	v_mfma_f32_16x16x32_bf16 v[58:61], v[156:159], v[180:183], v[58:61]
	v_mfma_f32_16x16x32_bf16 v[46:49], v[148:151], v[188:191], v[46:49]
	v_mfma_f32_16x16x32_bf16 v[42:45], v[156:159], v[188:191], v[42:45]
	v_mfma_f32_16x16x32_bf16 v[30:33], v[148:151], v[200:203], v[30:33]
	v_mfma_f32_16x16x32_bf16 v[26:29], v[156:159], v[200:203], v[26:29]
	v_mfma_f32_16x16x32_bf16 v[14:17], v[148:151], v[208:211], v[14:17]
	v_mfma_f32_16x16x32_bf16 v[10:13], v[156:159], v[208:211], v[10:13]
	v_mfma_f32_16x16x32_bf16 v[62:65], v[152:155], v[184:187], v[62:65]
	v_mfma_f32_16x16x32_bf16 v[58:61], v[160:163], v[184:187], v[58:61]
	v_mfma_f32_16x16x32_bf16 v[46:49], v[152:155], v[192:195], v[46:49]
	v_mfma_f32_16x16x32_bf16 v[42:45], v[160:163], v[192:195], v[42:45]
	v_mfma_f32_16x16x32_bf16 v[30:33], v[152:155], v[204:207], v[30:33]
	v_mfma_f32_16x16x32_bf16 v[26:29], v[160:163], v[204:207], v[26:29]
	v_mfma_f32_16x16x32_bf16 v[14:17], v[152:155], v[212:215], v[14:17]
	v_mfma_f32_16x16x32_bf16 v[10:13], v[160:163], v[212:215], v[10:13]
	s_setprio 0
	s_setprio 1
	v_mfma_f32_16x16x32_bf16 v[54:57], v[164:167], v[180:183], v[54:57]
	v_mfma_f32_16x16x32_bf16 v[50:53], v[172:175], v[180:183], v[50:53]
	v_mfma_f32_16x16x32_bf16 v[38:41], v[164:167], v[188:191], v[38:41]
	v_mfma_f32_16x16x32_bf16 v[34:37], v[172:175], v[188:191], v[34:37]
	v_mfma_f32_16x16x32_bf16 v[22:25], v[164:167], v[200:203], v[22:25]
	v_mfma_f32_16x16x32_bf16 v[18:21], v[172:175], v[200:203], v[18:21]
	v_mfma_f32_16x16x32_bf16 v[6:9], v[164:167], v[208:211], v[6:9]
	v_mfma_f32_16x16x32_bf16 v[2:5], v[172:175], v[208:211], v[2:5]
	v_mfma_f32_16x16x32_bf16 v[54:57], v[168:171], v[184:187], v[54:57]
	v_mfma_f32_16x16x32_bf16 v[50:53], v[176:179], v[184:187], v[50:53]
	v_mfma_f32_16x16x32_bf16 v[38:41], v[168:171], v[192:195], v[38:41]
	v_mfma_f32_16x16x32_bf16 v[34:37], v[176:179], v[192:195], v[34:37]
	v_mfma_f32_16x16x32_bf16 v[22:25], v[168:171], v[204:207], v[22:25]
	v_mfma_f32_16x16x32_bf16 v[18:21], v[176:179], v[204:207], v[18:21]
	v_mfma_f32_16x16x32_bf16 v[6:9], v[168:171], v[212:215], v[6:9]
	v_mfma_f32_16x16x32_bf16 v[2:5], v[176:179], v[212:215], v[2:5]
	s_setprio 0
	s_barrier
	s_add_u32 s34, s34, 0x100
	s_addc_u32 s35, s35, 0
	s_add_u32 s61, s61, 0x100
	s_addc_u32 s62, s62, 0
	s_cmp_ge_i32 s63, s51
	s_mov_b32 s36, s63
	s_cbranch_scc0 .LBB0_2194
	s_getpc_b64 s[98:99]
	s_mov_b32 m0, 0x22800
	v_lshlrev_b32_e32 v212, 7, v0
	global_load_lds_dword v212, s[98:99]
